# placement: 64-byte alignment (s_nop fill) in front of the 4 GEMM K-loop heads, attention tile loop and GLA chunk loop; on top of v44
# speedup vs baseline: 1.0032x; 1.0002x over previous
; #define PG8_STAGE(bufoff, gbase, voff) do { _Pragma("unroll") for (int _i = 0; _i < 2; ++_i) \
;         __builtin_amdgcn_global_load_lds((const unsigned*)((const char*)(gbase) + (voff)[_i]), (PG8_LAS unsigned*)(lds + (bufoff) + ldsw + _i * 8192), 16, 0, 0); } while (0)
; #define PG8_LDA(dst, b, h) do { _Pragma("unroll") for (int m = 0; m < 4; ++m) _Pragma("unroll") for (int k = 0; k < 2; ++k) dst[m][k] = *(const PG8_LAS bf16x8*)(lds + PG8_SA(b, h) + aoff + m * 2048 + k * 1024); } while (0)
; #define PG8_LDB(dst, b, h) do { _Pragma("unroll") for (int n = 0; n < 2; ++n) _Pragma("unroll") for (int k = 0; k < 2; ++k) dst[n][k] = *(const PG8_LAS bf16x8*)(lds + PG8_SB(b, h) + boff + n * 2048 + k * 1024); } while (0)
; #define PG8_MMA(ai, bj, At, Bt) do { __builtin_amdgcn_s_setprio(1); _Pragma("unroll") for (int m = 0; m < 4; ++m) _Pragma("unroll") for (int n = 0; n < 2; ++n) _Pragma("unroll") for (int k = 0; k < 2; ++k) \
;         acc[ai][bj][m][n] = __builtin_amdgcn_mfma_f32_16x16x32_bf16(Bt[n][k], At[m][k], acc[ai][bj][m][n], 0, 0, 0); __builtin_amdgcn_s_setprio(0); } while (0)
; template <class Epi, class Sched, bool ALIGN_EPI = false, bool SP2 = false>
; __device__ __forceinline__ void gemm_phase(PG8_LAS unsigned char* lds, const Gemm g, const Sched& S, const Epi& E) {
;     ...
;         const bool has_next = S.next(ui + 1, nxt);
;         const char* nA = has_next ? (const char*)g.A + (size_t)nxt.pm * tstep + (size_t)nxt.pn * g.a_gs : cA; const char* nB = has_next ? (const char*)g.Bt + (size_t)nxt.pn * tstep : cB;
;         for (int t = 0; t < nt; t += 2) {
;             const bool last = (t == nt - 2);
;             const char* a1 = cA + (size_t)(t + 1) * kstep;
;             const char* a2 = last ? nA : cA + (size_t)(t + 2) * kstep; const char* b2 = last ? nB : cB + (size_t)(t + 2) * kstep;
;             const char* a3 = a2 + kstep; const char* b3 = b2 + kstep;
;             if (last && has_next) S.a_ready(nxt);
;             if constexpr (SP2) {
;             PG8_LDB(B0, 0, 0); PG8_LDB(B1, 0, 1); PG8_SCHED; PG8_LDA(At, 0, 0); PG8_STAGE(PG8_SA(1, 1), a1 + hstep, voffA);
;             PG8_WAIT_V(8); PG8_WAIT_L(0); PG8_BAR; PG8_MMA(0, 0, At, B0); PG8_MMA(0, 1, At, B1); PG8_BAR; PG8_SCHED;
;             PG8_LDA(At, 0, 1); PG8_STAGE(PG8_SB(0, 0), b2, voffB); PG8_STAGE(PG8_SB(0, 1), b2 + hstep, voffB); PG8_STAGE(PG8_SA(0, 0), a2, voffA);
.LBB0_218:
	s_ashr_i32 s73, s72, 31
	s_lshl_b64 s[38:39], s[72:73], 19
	s_add_u32 s74, s10, s38
	s_addc_u32 s75, s11, s39
	s_and_b64 s[38:39], s[44:45], exec
	s_cselect_b32 s50, s75, s49
	s_cselect_b32 s51, s74, s48
	s_ashr_i32 s71, s70, 31
	s_lshl_b64 s[38:39], s[70:71], 19
	s_add_u32 s76, s62, s38
	s_addc_u32 s77, s63, s39
	s_and_b64 s[38:39], s[44:45], exec
	s_cselect_b32 s52, s77, s47
	s_cselect_b32 s53, s76, s46
	s_add_u32 s38, s48, 0x40080
	s_addc_u32 s39, s49, 0
	s_add_u32 s71, s46, 0x100
	s_addc_u32 s73, s47, 0
	s_mov_b32 vcc_lo, -2
	s_add_u32 s46, s38, 0xfffc0080
	s_addc_u32 s47, s39, -1
	s_add_i32 s56, 0, 0x10000
	s_cmp_eq_u32 vcc_lo, 12
	s_cselect_b32 s49, s50, s47
	s_cselect_b32 s48, s51, s46
	s_cselect_b32 s47, s52, s73
	s_cselect_b32 s46, s53, s71
	s_add_i32 vcc_hi, 0, 0x14000
	v_add_u32_e32 v152, s56, v165
	v_add_u32_e32 v169, vcc_hi, v165
	ds_read_b128 v[128:131], v152
	ds_read_b128 v[144:147], v152 offset:1024
	ds_read_b128 v[148:151], v152 offset:2048
	ds_read_b128 v[152:155], v152 offset:3072
	ds_read_b128 v[156:159], v169
	ds_read_b128 v[160:163], v169 offset:1024
	ds_read_b128 v[170:173], v169 offset:2048
	ds_read_b128 v[180:183], v169 offset:3072
	v_lshl_add_u64 v[176:177], s[38:39], 0, v[140:141]
	s_add_i32 m0, s9, 0xc000
	ds_read_b128 v[184:187], v168
	ds_read_b128 v[188:191], v168 offset:1024
	ds_read_b128 v[192:195], v168 offset:2048
	ds_read_b128 v[196:199], v168 offset:3072
	ds_read_b128 v[200:203], v168 offset:4096
	ds_read_b128 v[204:207], v168 offset:5120
	ds_read_b128 v[218:221], v168 offset:6144
	ds_read_b128 v[222:225], v168 offset:7168
	global_load_lds_dwordx4 v[176:177], off
	v_lshl_add_u64 v[176:177], s[38:39], 0, v[142:143]
	s_add_i32 m0, s9, 0xe000
	s_nop 0
	global_load_lds_dwordx4 v[176:177], off
	s_waitcnt vmcnt(8)
	s_waitcnt lgkmcnt(0)
	s_setprio 1
	s_barrier
	v_mfma_f32_16x16x32_bf16 v[124:127], v[128:131], v[184:187], 0
	v_mfma_f32_16x16x32_bf16 v[120:123], v[148:151], v[184:187], 0
	v_mfma_f32_16x16x32_bf16 v[108:111], v[128:131], v[192:195], 0
	v_mfma_f32_16x16x32_bf16 v[104:107], v[148:151], v[192:195], 0
	v_mfma_f32_16x16x32_bf16 v[92:95], v[128:131], v[200:203], 0
	v_mfma_f32_16x16x32_bf16 v[88:91], v[148:151], v[200:203], 0
	v_mfma_f32_16x16x32_bf16 v[76:79], v[128:131], v[218:221], 0
	v_mfma_f32_16x16x32_bf16 v[72:75], v[148:151], v[218:221], 0
	v_mfma_f32_16x16x32_bf16 v[124:127], v[144:147], v[188:191], v[124:127]
	v_mfma_f32_16x16x32_bf16 v[120:123], v[152:155], v[188:191], v[120:123]
	v_mfma_f32_16x16x32_bf16 v[108:111], v[144:147], v[196:199], v[108:111]
	v_mfma_f32_16x16x32_bf16 v[104:107], v[152:155], v[196:199], v[104:107]
	v_mfma_f32_16x16x32_bf16 v[92:95], v[144:147], v[204:207], v[92:95]
	v_mfma_f32_16x16x32_bf16 v[88:91], v[152:155], v[204:207], v[88:91]
	v_mfma_f32_16x16x32_bf16 v[76:79], v[144:147], v[222:225], v[76:79]
	v_mfma_f32_16x16x32_bf16 v[72:75], v[152:155], v[222:225], v[72:75]
	v_mfma_f32_16x16x32_bf16 v[116:119], v[156:159], v[184:187], 0
	v_mfma_f32_16x16x32_bf16 v[112:115], v[170:173], v[184:187], 0
	v_mfma_f32_16x16x32_bf16 v[100:103], v[156:159], v[192:195], 0
	v_mfma_f32_16x16x32_bf16 v[96:99], v[170:173], v[192:195], 0
	v_mfma_f32_16x16x32_bf16 v[84:87], v[156:159], v[200:203], 0
	v_mfma_f32_16x16x32_bf16 v[80:83], v[170:173], v[200:203], 0
	v_mfma_f32_16x16x32_bf16 v[68:71], v[156:159], v[218:221], 0
	v_mfma_f32_16x16x32_bf16 v[64:67], v[170:173], v[218:221], 0
	v_mfma_f32_16x16x32_bf16 v[116:119], v[160:163], v[188:191], v[116:119]
	v_mfma_f32_16x16x32_bf16 v[112:115], v[180:183], v[188:191], v[112:115]
	v_mfma_f32_16x16x32_bf16 v[100:103], v[160:163], v[196:199], v[100:103]
	v_mfma_f32_16x16x32_bf16 v[96:99], v[180:183], v[196:199], v[96:99]
	v_mfma_f32_16x16x32_bf16 v[84:87], v[160:163], v[204:207], v[84:87]
	v_mfma_f32_16x16x32_bf16 v[80:83], v[180:183], v[204:207], v[80:83]
	v_mfma_f32_16x16x32_bf16 v[68:71], v[160:163], v[222:225], v[68:71]
	v_mfma_f32_16x16x32_bf16 v[64:67], v[180:183], v[222:225], v[64:67]
	s_barrier
	s_setprio 0
	s_add_i32 s56, s56, s8
	v_lshl_add_u64 v[176:177], s[46:47], 0, v[174:175]
	s_mov_b32 m0, s56
	ds_read_b128 v[184:187], v168 offset:16384
	ds_read_b128 v[188:191], v168 offset:17408
	ds_read_b128 v[192:195], v168 offset:18432
	ds_read_b128 v[196:199], v168 offset:19456
	ds_read_b128 v[200:203], v168 offset:20480
	ds_read_b128 v[204:207], v168 offset:21504
	ds_read_b128 v[218:221], v168 offset:22528
	ds_read_b128 v[222:225], v168 offset:23552
	global_load_lds_dwordx4 v[176:177], off
	s_add_i32 m0, s56, 0x2000
	s_add_u32 s56, s46, 0x40000
	v_lshl_add_u64 v[178:179], s[46:47], 0, v[136:137]
	s_addc_u32 s57, s47, 0
	s_add_i32 vcc_hi, vcc_hi, s8
	global_load_lds_dwordx4 v[178:179], off
	v_lshl_add_u64 v[208:209], s[56:57], 0, v[174:175]
	s_mov_b32 m0, vcc_hi
	v_lshl_add_u64 v[226:227], s[48:49], 0, v[134:135]
	global_load_lds_dwordx4 v[208:209], off
	v_lshl_add_u64 v[208:209], s[56:57], 0, v[136:137]
	s_add_i32 m0, vcc_hi, 0x2000
	s_nop 0
	global_load_lds_dwordx4 v[208:209], off
	v_lshl_add_u64 v[208:209], s[48:49], 0, v[132:133]
	s_mov_b32 m0, s9
	s_nop 0
	global_load_lds_dwordx4 v[208:209], off
	s_mov_b32 m0, s79
	s_nop 0
	global_load_lds_dwordx4 v[226:227], off
	s_waitcnt vmcnt(8)
	s_waitcnt lgkmcnt(0)
	s_setprio 1
	s_barrier
; #define PG8_STAGE(bufoff, gbase, voff) do { _Pragma("unroll") for (int _i = 0; _i < 2; ++_i) \
;         __builtin_amdgcn_global_load_lds((const unsigned*)((const char*)(gbase) + (voff)[_i]), (PG8_LAS unsigned*)(lds + (bufoff) + ldsw + _i * 8192), 16, 0, 0); } while (0)
; #define PG8_LDA(dst, b, h) do { _Pragma("unroll") for (int m = 0; m < 4; ++m) _Pragma("unroll") for (int k = 0; k < 2; ++k) dst[m][k] = *(const PG8_LAS bf16x8*)(lds + PG8_SA(b, h) + aoff + m * 2048 + k * 1024); } while (0)
; #define PG8_LDB(dst, b, h) do { _Pragma("unroll") for (int n = 0; n < 2; ++n) _Pragma("unroll") for (int k = 0; k < 2; ++k) dst[n][k] = *(const PG8_LAS bf16x8*)(lds + PG8_SB(b, h) + boff + n * 2048 + k * 1024); } while (0)
; #define PG8_MMA(ai, bj, At, Bt) do { __builtin_amdgcn_s_setprio(1); _Pragma("unroll") for (int m = 0; m < 4; ++m) _Pragma("unroll") for (int n = 0; n < 2; ++n) _Pragma("unroll") for (int k = 0; k < 2; ++k) \
;         acc[ai][bj][m][n] = __builtin_amdgcn_mfma_f32_16x16x32_bf16(Bt[n][k], At[m][k], acc[ai][bj][m][n], 0, 0, 0); __builtin_amdgcn_s_setprio(0); } while (0)
; #define PG8_WAIT_V(n) asm volatile("s_waitcnt vmcnt(" #n ")" ::: "memory")
; #define PG8_WAIT_L(n) asm volatile("s_waitcnt lgkmcnt(" #n ")" ::: "memory")
; #define PG8_BAR __builtin_amdgcn_s_barrier()
; #define PG8_SCHED __builtin_amdgcn_sched_barrier(0)
; template <class Epi, class Sched, bool ALIGN_EPI = false, bool SP2 = false>
; __device__ __forceinline__ void gemm_phase(PG8_LAS unsigned char* lds, const Gemm g, const Sched& S, const Epi& E) {
;     ...
;             PG8_WAIT_V(8); PG8_WAIT_L(0); PG8_BAR; PG8_MMA(1, 0, At, B0); PG8_MMA(1, 1, At, B1); PG8_BAR; PG8_SCHED;
;             PG8_LDB(B0, 1, 0); PG8_LDB(B1, 1, 1); PG8_SCHED; PG8_LDA(At, 1, 0); PG8_STAGE(PG8_SA(0, 1), a2 + hstep, voffA);
;             PG8_WAIT_V(8); PG8_WAIT_L(0); PG8_BAR; PG8_MMA(0, 0, At, B0); PG8_MMA(0, 1, At, B1); PG8_BAR; PG8_SCHED;
	v_mfma_f32_16x16x32_bf16 v[60:63], v[128:131], v[184:187], 0
	v_mfma_f32_16x16x32_bf16 v[56:59], v[148:151], v[184:187], 0
	v_mfma_f32_16x16x32_bf16 v[44:47], v[128:131], v[192:195], 0
	v_mfma_f32_16x16x32_bf16 v[40:43], v[148:151], v[192:195], 0
	v_mfma_f32_16x16x32_bf16 v[28:31], v[128:131], v[200:203], 0
	v_mfma_f32_16x16x32_bf16 v[24:27], v[148:151], v[200:203], 0
	v_mfma_f32_16x16x32_bf16 v[12:15], v[128:131], v[218:221], 0
	v_mfma_f32_16x16x32_bf16 v[8:11], v[148:151], v[218:221], 0
	v_mfma_f32_16x16x32_bf16 v[60:63], v[144:147], v[188:191], v[60:63]
	v_mfma_f32_16x16x32_bf16 v[56:59], v[152:155], v[188:191], v[56:59]
	v_mfma_f32_16x16x32_bf16 v[44:47], v[144:147], v[196:199], v[44:47]
	v_mfma_f32_16x16x32_bf16 v[40:43], v[152:155], v[196:199], v[40:43]
	v_mfma_f32_16x16x32_bf16 v[28:31], v[144:147], v[204:207], v[28:31]
	v_mfma_f32_16x16x32_bf16 v[24:27], v[152:155], v[204:207], v[24:27]
	v_mfma_f32_16x16x32_bf16 v[12:15], v[144:147], v[222:225], v[12:15]
	v_mfma_f32_16x16x32_bf16 v[8:11], v[152:155], v[222:225], v[8:11]
	v_mfma_f32_16x16x32_bf16 v[52:55], v[156:159], v[184:187], 0
	v_mfma_f32_16x16x32_bf16 v[48:51], v[170:173], v[184:187], 0
	v_mfma_f32_16x16x32_bf16 v[36:39], v[156:159], v[192:195], 0
	v_mfma_f32_16x16x32_bf16 v[32:35], v[170:173], v[192:195], 0
	v_mfma_f32_16x16x32_bf16 v[20:23], v[156:159], v[200:203], 0
	v_mfma_f32_16x16x32_bf16 v[16:19], v[170:173], v[200:203], 0
	v_mfma_f32_16x16x32_bf16 v[4:7], v[156:159], v[218:221], 0
	v_mfma_f32_16x16x32_bf16 v[0:3], v[170:173], v[218:221], 0
	v_mfma_f32_16x16x32_bf16 v[52:55], v[160:163], v[188:191], v[52:55]
	v_mfma_f32_16x16x32_bf16 v[48:51], v[180:183], v[188:191], v[48:51]
	v_mfma_f32_16x16x32_bf16 v[36:39], v[160:163], v[196:199], v[36:39]
	v_mfma_f32_16x16x32_bf16 v[32:35], v[180:183], v[196:199], v[32:35]
	v_mfma_f32_16x16x32_bf16 v[20:23], v[160:163], v[204:207], v[20:23]
	v_mfma_f32_16x16x32_bf16 v[16:19], v[180:183], v[204:207], v[16:19]
	v_mfma_f32_16x16x32_bf16 v[4:7], v[160:163], v[222:225], v[4:7]
	v_mfma_f32_16x16x32_bf16 v[0:3], v[180:183], v[222:225], v[0:3]
	s_barrier
	s_setprio 0
	s_add_i32 s56, 0, 0x18000
	s_add_i32 s57, 0, 0x1c000
	v_add_u32_e32 v152, s56, v165
	v_add_u32_e32 v169, s57, v165
	ds_read_b128 v[128:131], v152
	ds_read_b128 v[144:147], v152 offset:1024
	ds_read_b128 v[148:151], v152 offset:2048
	ds_read_b128 v[152:155], v152 offset:3072
	ds_read_b128 v[156:159], v169
	ds_read_b128 v[160:163], v169 offset:1024
	ds_read_b128 v[170:173], v169 offset:2048
	ds_read_b128 v[180:183], v169 offset:3072
	s_add_u32 s48, s48, 0x40000
	s_addc_u32 s49, s49, 0
	s_mov_b32 m0, s54
	v_lshl_add_u64 v[228:229], s[48:49], 0, v[132:133]
	ds_read_b128 v[184:187], v168 offset:32768
	ds_read_b128 v[188:191], v168 offset:33792
	ds_read_b128 v[192:195], v168 offset:34816
	ds_read_b128 v[196:199], v168 offset:35840
	ds_read_b128 v[200:203], v168 offset:36864
	ds_read_b128 v[204:207], v168 offset:37888
	ds_read_b128 v[218:221], v168 offset:38912
	ds_read_b128 v[222:225], v168 offset:39936
	global_load_lds_dwordx4 v[228:229], off
	v_lshl_add_u64 v[228:229], s[48:49], 0, v[134:135]
	s_mov_b32 m0, s55
	s_nop 0
	global_load_lds_dwordx4 v[228:229], off
	s_waitcnt vmcnt(8)
	s_waitcnt lgkmcnt(0)
	s_setprio 1
	s_barrier
	v_mfma_f32_16x16x32_bf16 v[124:127], v[128:131], v[184:187], v[124:127]
	v_mfma_f32_16x16x32_bf16 v[120:123], v[148:151], v[184:187], v[120:123]
	v_mfma_f32_16x16x32_bf16 v[108:111], v[128:131], v[192:195], v[108:111]
	v_mfma_f32_16x16x32_bf16 v[104:107], v[148:151], v[192:195], v[104:107]
	v_mfma_f32_16x16x32_bf16 v[92:95], v[128:131], v[200:203], v[92:95]
	v_mfma_f32_16x16x32_bf16 v[88:91], v[148:151], v[200:203], v[88:91]
	v_mfma_f32_16x16x32_bf16 v[76:79], v[128:131], v[218:221], v[76:79]
	v_mfma_f32_16x16x32_bf16 v[72:75], v[148:151], v[218:221], v[72:75]
	v_mfma_f32_16x16x32_bf16 v[124:127], v[144:147], v[188:191], v[124:127]
	v_mfma_f32_16x16x32_bf16 v[120:123], v[152:155], v[188:191], v[120:123]
	v_mfma_f32_16x16x32_bf16 v[108:111], v[144:147], v[196:199], v[108:111]
	v_mfma_f32_16x16x32_bf16 v[104:107], v[152:155], v[196:199], v[104:107]
	v_mfma_f32_16x16x32_bf16 v[92:95], v[144:147], v[204:207], v[92:95]
	v_mfma_f32_16x16x32_bf16 v[88:91], v[152:155], v[204:207], v[88:91]
	v_mfma_f32_16x16x32_bf16 v[76:79], v[144:147], v[222:225], v[76:79]
	v_mfma_f32_16x16x32_bf16 v[72:75], v[152:155], v[222:225], v[72:75]
	v_mfma_f32_16x16x32_bf16 v[116:119], v[156:159], v[184:187], v[116:119]
	v_mfma_f32_16x16x32_bf16 v[112:115], v[170:173], v[184:187], v[112:115]
	v_mfma_f32_16x16x32_bf16 v[100:103], v[156:159], v[192:195], v[100:103]
	v_mfma_f32_16x16x32_bf16 v[96:99], v[170:173], v[192:195], v[96:99]
	v_mfma_f32_16x16x32_bf16 v[84:87], v[156:159], v[200:203], v[84:87]
	v_mfma_f32_16x16x32_bf16 v[80:83], v[170:173], v[200:203], v[80:83]
	v_mfma_f32_16x16x32_bf16 v[68:71], v[156:159], v[218:221], v[68:71]
	v_mfma_f32_16x16x32_bf16 v[64:67], v[170:173], v[218:221], v[64:67]
	v_mfma_f32_16x16x32_bf16 v[116:119], v[160:163], v[188:191], v[116:119]
	v_mfma_f32_16x16x32_bf16 v[112:115], v[180:183], v[188:191], v[112:115]
	v_mfma_f32_16x16x32_bf16 v[100:103], v[160:163], v[196:199], v[100:103]
	v_mfma_f32_16x16x32_bf16 v[96:99], v[180:183], v[196:199], v[96:99]
	v_mfma_f32_16x16x32_bf16 v[84:87], v[160:163], v[204:207], v[84:87]
	v_mfma_f32_16x16x32_bf16 v[80:83], v[180:183], v[204:207], v[80:83]
	v_mfma_f32_16x16x32_bf16 v[68:71], v[160:163], v[222:225], v[68:71]
	v_mfma_f32_16x16x32_bf16 v[64:67], v[180:183], v[222:225], v[64:67]
	s_barrier
; #define PG8_STAGE(bufoff, gbase, voff) do { _Pragma("unroll") for (int _i = 0; _i < 2; ++_i) \
;         __builtin_amdgcn_global_load_lds((const unsigned*)((const char*)(gbase) + (voff)[_i]), (PG8_LAS unsigned*)(lds + (bufoff) + ldsw + _i * 8192), 16, 0, 0); } while (0)
; #define PG8_LDA(dst, b, h) do { _Pragma("unroll") for (int m = 0; m < 4; ++m) _Pragma("unroll") for (int k = 0; k < 2; ++k) dst[m][k] = *(const PG8_LAS bf16x8*)(lds + PG8_SA(b, h) + aoff + m * 2048 + k * 1024); } while (0)
; #define PG8_MMA(ai, bj, At, Bt) do { __builtin_amdgcn_s_setprio(1); _Pragma("unroll") for (int m = 0; m < 4; ++m) _Pragma("unroll") for (int n = 0; n < 2; ++n) _Pragma("unroll") for (int k = 0; k < 2; ++k) \
;         acc[ai][bj][m][n] = __builtin_amdgcn_mfma_f32_16x16x32_bf16(Bt[n][k], At[m][k], acc[ai][bj][m][n], 0, 0, 0); __builtin_amdgcn_s_setprio(0); } while (0)
; #define PG8_WAIT_V(n) asm volatile("s_waitcnt vmcnt(" #n ")" ::: "memory")
; #define PG8_WAIT_L(n) asm volatile("s_waitcnt lgkmcnt(" #n ")" ::: "memory")
; #define PG8_BAR __builtin_amdgcn_s_barrier()
; #define PG8_SCHED __builtin_amdgcn_sched_barrier(0)
; template <class Epi, class Sched, bool ALIGN_EPI = false, bool SP2 = false>
; __device__ __forceinline__ void gemm_phase(PG8_LAS unsigned char* lds, const Gemm g, const Sched& S, const Epi& E) {
;     ...
;             PG8_LDA(At, 1, 1); PG8_STAGE(PG8_SB(1, 0), b3, voffB); PG8_STAGE(PG8_SB(1, 1), b3 + hstep, voffB); PG8_STAGE(PG8_SA(1, 0), a3, voffA);
;             PG8_WAIT_V(8); PG8_WAIT_L(0); PG8_BAR; PG8_MMA(1, 0, At, B0); PG8_MMA(1, 1, At, B1); PG8_BAR; PG8_SCHED;
	s_setprio 0
	s_add_i32 s48, s56, s8
	v_lshl_add_u64 v[176:177], v[176:177], 0, s[4:5]
	s_mov_b32 m0, s48
	ds_read_b128 v[184:187], v168 offset:49152
	ds_read_b128 v[188:191], v168 offset:50176
	ds_read_b128 v[192:195], v168 offset:51200
	ds_read_b128 v[196:199], v168 offset:52224
	ds_read_b128 v[200:203], v168 offset:53248
	ds_read_b128 v[204:207], v168 offset:54272
	ds_read_b128 v[218:221], v168 offset:55296
	ds_read_b128 v[222:225], v168 offset:56320
	global_load_lds_dwordx4 v[176:177], off
	s_add_i32 m0, s48, 0x2000
	s_add_u32 s46, s46, 0x40080
	v_lshl_add_u64 v[176:177], v[178:179], 0, s[4:5]
	s_addc_u32 s47, s47, 0
	s_add_i32 s48, s57, s8
	global_load_lds_dwordx4 v[176:177], off
	v_lshl_add_u64 v[176:177], s[46:47], 0, v[174:175]
	s_mov_b32 m0, s48
	s_nop 0
	global_load_lds_dwordx4 v[176:177], off
	v_lshl_add_u64 v[176:177], s[46:47], 0, v[136:137]
	s_add_i32 m0, s48, 0x2000
	s_nop 0
	global_load_lds_dwordx4 v[176:177], off
	v_lshl_add_u64 v[176:177], v[208:209], 0, s[4:5]
	s_mov_b32 m0, s93
	s_nop 0
	global_load_lds_dwordx4 v[176:177], off
	v_lshl_add_u64 v[176:177], v[226:227], 0, s[4:5]
	s_mov_b32 m0, s66
	s_nop 0
	global_load_lds_dwordx4 v[176:177], off
	s_waitcnt vmcnt(8)
	s_waitcnt lgkmcnt(0)
	s_setprio 1
	s_barrier
	v_mfma_f32_16x16x32_bf16 v[60:63], v[128:131], v[184:187], v[60:63]
	v_mfma_f32_16x16x32_bf16 v[56:59], v[148:151], v[184:187], v[56:59]
	v_mfma_f32_16x16x32_bf16 v[44:47], v[128:131], v[192:195], v[44:47]
	v_mfma_f32_16x16x32_bf16 v[40:43], v[148:151], v[192:195], v[40:43]
	v_mfma_f32_16x16x32_bf16 v[28:31], v[128:131], v[200:203], v[28:31]
	v_mfma_f32_16x16x32_bf16 v[24:27], v[148:151], v[200:203], v[24:27]
	v_mfma_f32_16x16x32_bf16 v[12:15], v[128:131], v[218:221], v[12:15]
	v_mfma_f32_16x16x32_bf16 v[8:11], v[148:151], v[218:221], v[8:11]
	v_mfma_f32_16x16x32_bf16 v[60:63], v[144:147], v[188:191], v[60:63]
	v_mfma_f32_16x16x32_bf16 v[56:59], v[152:155], v[188:191], v[56:59]
	v_mfma_f32_16x16x32_bf16 v[44:47], v[144:147], v[196:199], v[44:47]
	v_mfma_f32_16x16x32_bf16 v[40:43], v[152:155], v[196:199], v[40:43]
	v_mfma_f32_16x16x32_bf16 v[28:31], v[144:147], v[204:207], v[28:31]
	v_mfma_f32_16x16x32_bf16 v[24:27], v[152:155], v[204:207], v[24:27]
	v_mfma_f32_16x16x32_bf16 v[12:15], v[144:147], v[222:225], v[12:15]
	v_mfma_f32_16x16x32_bf16 v[8:11], v[152:155], v[222:225], v[8:11]
	v_mfma_f32_16x16x32_bf16 v[52:55], v[156:159], v[184:187], v[52:55]
	v_mfma_f32_16x16x32_bf16 v[48:51], v[170:173], v[184:187], v[48:51]
	v_mfma_f32_16x16x32_bf16 v[36:39], v[156:159], v[192:195], v[36:39]
	v_mfma_f32_16x16x32_bf16 v[32:35], v[170:173], v[192:195], v[32:35]
	v_mfma_f32_16x16x32_bf16 v[20:23], v[156:159], v[200:203], v[20:23]
	v_mfma_f32_16x16x32_bf16 v[16:19], v[170:173], v[200:203], v[16:19]
	v_mfma_f32_16x16x32_bf16 v[4:7], v[156:159], v[218:221], v[4:7]
	v_mfma_f32_16x16x32_bf16 v[0:3], v[170:173], v[218:221], v[0:3]
	v_mfma_f32_16x16x32_bf16 v[52:55], v[160:163], v[188:191], v[52:55]
	v_mfma_f32_16x16x32_bf16 v[48:51], v[180:183], v[188:191], v[48:51]
	v_mfma_f32_16x16x32_bf16 v[36:39], v[160:163], v[196:199], v[36:39]
	v_mfma_f32_16x16x32_bf16 v[32:35], v[180:183], v[196:199], v[32:35]
	v_mfma_f32_16x16x32_bf16 v[20:23], v[160:163], v[204:207], v[20:23]
	v_mfma_f32_16x16x32_bf16 v[16:19], v[180:183], v[204:207], v[16:19]
	v_mfma_f32_16x16x32_bf16 v[4:7], v[160:163], v[222:225], v[4:7]
	v_mfma_f32_16x16x32_bf16 v[0:3], v[180:183], v[222:225], v[0:3]
	s_barrier
	s_setprio 0
	s_add_i32 vcc_lo, vcc_lo, 2
	s_add_u32 s38, s38, 0x100
	s_addc_u32 s39, s39, 0
	s_add_u32 s71, s71, 0x100
	s_addc_u32 s73, s73, 0
	s_cmp_gt_u32 vcc_lo, 13
	s_cbranch_scc0 .LBB0_219
	.p2alignl 6, 3212836864

; __device__ __forceinline__ void attn_phase(LAS unsigned char* lds, const bf16_t* QKV, const float* kmean, const float* biasT, bf16_t* O, int G, int wg) {
;     ...
;         const int nTiles = 4 + ob * 4;
;         float m_run[2] = {-1e30f, -1e30f}, l_run[2] = {0.f, 0.f};
;         f32x4 oacc[2][8];
; #pragma unroll
;         for (int z = 0; z < 2; ++z)
; #pragma unroll
;             for (int e = 0; e < 8; ++e) oacc[z][e] = (f32x4){0.f, 0.f, 0.f, 0.f};
;         ATT_STAGE(0);
;         ATT_LOAD(1);
;         const bool skew = wid >= 4;
;         bf16x8 pf[2][2]; bool pend = false; int pend_buf = 0, cur = 0;
.LBB0_1350:
	s_or_b32 s0, s0, 64
	s_mov_b32 s1, s17
	v_lshl_add_u64 v[48:49], s[0:1], 0, v[146:147]
	v_mov_b64_e32 v[50:51], s[14:15]
	v_mad_u64_u32 v[52:53], s[38:39], v48, s89, v[50:51]
	v_mad_i32_i24 v53, v49, s89, v53
	v_lshl_add_u64 v[48:49], v[52:53], 0, s[16:17]
	v_or_b32_e32 v52, s0, v144
	v_mad_u64_u32 v[50:51], s[0:1], v52, s89, v[50:51]
	v_lshl_add_u64 v[50:51], v[50:51], 0, s[16:17]
	v_lshl_add_u64 v[48:49], v[48:49], 0, v[174:175]
	v_lshl_add_u64 v[50:51], v[148:149], 1, v[50:51]
	s_movk_i32 s0, 0x1000
	global_load_dwordx4 v[96:99], v[48:49], off offset:2064
	global_load_dwordx4 v[100:103], v[48:49], off offset:2048
	v_add_co_u32_e32 v48, vcc, s0, v50
	v_lshl_add_u64 v[52:53], v[50:51], 0, s[94:95]
	s_nop 0
	v_addc_co_u32_e32 v49, vcc, 0, v51, vcc
	global_load_dwordx4 v[104:107], v[48:49], off
	global_load_dwordx4 v[108:111], v[52:53], off offset:16
	v_add_u32_e32 v49, 0, v208
	v_add_u32_e32 v48, v49, v217
	s_waitcnt vmcnt(14)
	ds_write_b128 v48, v[44:47]
	v_add_u32_e32 v44, v49, v218
	ds_write_b128 v44, v[40:43]
	s_waitcnt vmcnt(13)
	ds_write_b16 v228, v32 offset:16384
	s_waitcnt vmcnt(12)
	ds_write_b16 v228, v36 offset:17472
	ds_write_b16_d16_hi v228, v32 offset:16520
	ds_write_b16_d16_hi v228, v36 offset:17608
	ds_write_b16 v228, v33 offset:16656
	ds_write_b16 v228, v37 offset:17744
	ds_write_b16_d16_hi v228, v33 offset:16792
	ds_write_b16_d16_hi v228, v37 offset:17880
	ds_write_b16 v228, v34 offset:16928
	ds_write_b16 v228, v38 offset:18016
	ds_write_b16_d16_hi v228, v34 offset:17064
	ds_write_b16_d16_hi v228, v38 offset:18152
	ds_write_b16 v228, v35 offset:17200
	ds_write_b16 v228, v39 offset:18288
	ds_write_b16_d16_hi v228, v35 offset:17336
	ds_write_b16_d16_hi v228, v39 offset:18424
	v_mov_b32_e32 v34, v175
	v_mov_b32_e32 v35, v175
	s_lshl_b32 s47, s54, 2
	v_or_b32_e32 v182, 16, v180
	v_mov_b32_e32 v32, v175
	v_mov_b32_e32 v33, v175
	v_mov_b64_e32 v[38:39], v[34:35]
	v_mov_b64_e32 v[42:43], v[34:35]
	v_mov_b64_e32 v[46:47], v[34:35]
	v_mov_b64_e32 v[50:51], v[34:35]
	v_mov_b64_e32 v[54:55], v[34:35]
	v_mov_b64_e32 v[58:59], v[34:35]
	v_mov_b64_e32 v[62:63], v[34:35]
	v_mov_b64_e32 v[66:67], v[34:35]
	v_mov_b64_e32 v[70:71], v[34:35]
	v_mov_b64_e32 v[74:75], v[34:35]
	v_mov_b64_e32 v[78:79], v[34:35]
	v_mov_b64_e32 v[82:83], v[34:35]
	v_mov_b64_e32 v[86:87], v[34:35]
	v_mov_b64_e32 v[90:91], v[34:35]
	v_mov_b64_e32 v[94:95], v[34:35]
	s_add_i32 s55, s47, 4
	s_mov_b32 s56, 0
	v_mov_b32_e32 v163, v182
	v_mov_b32_e32 v165, v180
	v_lshl_add_u64 v[184:185], v[166:167], 0, s[16:17]
	s_mov_b64 s[38:39], 0
	v_mov_b32_e32 v181, 0
	v_mov_b32_e32 v233, 0xf149f2ca
	s_mov_b32 s57, -4
	v_mov_b32_e32 v232, 0
	v_mov_b32_e32 v202, 0xf149f2ca
	v_mov_b32_e32 v229, 0
	v_mov_b64_e32 v[36:37], v[32:33]
	v_mov_b64_e32 v[40:41], v[32:33]
	v_mov_b64_e32 v[44:45], v[32:33]
	v_mov_b64_e32 v[48:49], v[32:33]
	v_mov_b64_e32 v[52:53], v[32:33]
	v_mov_b64_e32 v[56:57], v[32:33]
	v_mov_b64_e32 v[60:61], v[32:33]
	v_mov_b64_e32 v[64:65], v[32:33]
	v_mov_b64_e32 v[68:69], v[32:33]
	v_mov_b64_e32 v[72:73], v[32:33]
	v_mov_b64_e32 v[76:77], v[32:33]
	v_mov_b64_e32 v[80:81], v[32:33]
	v_mov_b64_e32 v[84:85], v[32:33]
	v_mov_b64_e32 v[88:89], v[32:33]
	v_mov_b64_e32 v[92:93], v[32:33]
	s_mov_b32 s59, 0
	.p2alignl 6, 3212836864

; #define LAS __attribute__((address_space(3)))
; #define MFMA16(a, b, c) __builtin_amdgcn_mfma_f32_16x16x32_bf16((a), (b), (c), 0, 0, 0)
; __device__ __forceinline__ void gla_phase(LAS unsigned char* lds, const bf16_t* P, const float* hn, bf16_t* O, int G, int wg) {
;     ...
;               f32x4 dec4, cl4;
;               { f32x4 bm4 = (f32x4){0.f, 0.f, 0.f, 0.f}, bl4 = (f32x4){0.f, 0.f, 0.f, 0.f};
; #pragma unroll
;                 for (int s2 = 0; s2 < 8; ++s2) { const f32x4 p = *(const LAS f32x4*)(lds + PART + (s2 * 128 + wid * 16 + fq * 4) * 4); if (s2 < 4) bm4 += p; bl4 += p; }
; #pragma unroll
;                 for (int j = 0; j < 4; ++j) { dec4[j] = __builtin_amdgcn_exp2f(bl4[j]); cl4[j] = __builtin_amdgcn_exp2f(bl4[j] - bm4[j]); } }
; #pragma unroll
;               for (int e = 0; e < 8; ++e) { f32x4 tmp = (f32x4){0.f, 0.f, 0.f, 0.f};
; #pragma unroll
;                 for (int ks = 0; ks < 2; ++ks) tmp = MFMA16(kD[ks], (e < 4) ? vO[e & 3][ks] : vX[e & 3][ks], tmp);
;                 sacc[e] = sacc[e] * dec4 + tmp * cl4; }
.LBB0_1401:
	s_or_b64 exec, exec, vcc
	s_waitcnt lgkmcnt(8)
	v_pk_add_f32 v[62:63], v[62:63], 0 op_sel_hi:[1,0]
	v_pk_add_f32 v[60:61], v[60:61], 0 op_sel_hi:[1,0]
	s_waitcnt lgkmcnt(7)
	v_pk_add_f32 v[58:59], v[62:63], v[58:59]
	v_pk_add_f32 v[56:57], v[60:61], v[56:57]
	s_waitcnt lgkmcnt(5)
	v_pk_add_f32 v[54:55], v[58:59], v[54:55]
	v_pk_add_f32 v[52:53], v[56:57], v[52:53]
	s_waitcnt lgkmcnt(4)
	v_pk_add_f32 v[50:51], v[54:55], v[50:51]
	v_pk_add_f32 v[48:49], v[52:53], v[48:49]
	s_waitcnt lgkmcnt(3)
	v_pk_add_f32 v[52:53], v[50:51], v[78:79]
	v_pk_add_f32 v[54:55], v[48:49], v[76:77]
	s_waitcnt lgkmcnt(2)
	v_pk_add_f32 v[52:53], v[52:53], v[74:75]
	v_pk_add_f32 v[54:55], v[54:55], v[72:73]
	s_waitcnt lgkmcnt(1)
	v_pk_add_f32 v[52:53], v[52:53], v[70:71]
	v_pk_add_f32 v[54:55], v[54:55], v[68:69]
	s_waitcnt lgkmcnt(0)
	v_pk_add_f32 v[52:53], v[52:53], v[66:67]
	v_pk_add_f32 v[54:55], v[54:55], v[64:65]
	v_sub_f32_e32 v50, v52, v50
	v_sub_f32_e32 v48, v54, v48
	v_sub_f32_e32 v49, v55, v49
	v_sub_f32_e32 v51, v53, v51
	v_exp_f32_e32 v48, v48
	v_exp_f32_e32 v49, v49
	v_exp_f32_e32 v50, v50
	v_exp_f32_e32 v51, v51
	v_exp_f32_e32 v56, v54
	v_exp_f32_e32 v52, v52
	v_exp_f32_e32 v53, v53
	v_exp_f32_e32 v57, v55
	v_pk_mul_f32 v[18:19], v[18:19], v[50:51]
	v_pk_mul_f32 v[16:17], v[16:17], v[48:49]
	v_pk_fma_f32 v[108:109], v[108:109], v[52:53], v[18:19]
	v_pk_fma_f32 v[106:107], v[106:107], v[56:57], v[16:17]
	v_pk_mul_f32 v[16:17], v[22:23], v[50:51]
	v_pk_mul_f32 v[18:19], v[20:21], v[48:49]
	v_pk_fma_f32 v[112:113], v[112:113], v[52:53], v[16:17]
	v_pk_fma_f32 v[110:111], v[110:111], v[56:57], v[18:19]
	v_pk_mul_f32 v[16:17], v[26:27], v[50:51]
	v_pk_mul_f32 v[18:19], v[24:25], v[48:49]
	v_pk_fma_f32 v[118:119], v[118:119], v[52:53], v[16:17]
	v_pk_fma_f32 v[116:117], v[116:117], v[56:57], v[18:19]
	v_pk_mul_f32 v[16:17], v[50:51], v[30:31]
	v_pk_mul_f32 v[18:19], v[48:49], v[28:29]
	v_pk_fma_f32 v[122:123], v[122:123], v[52:53], v[16:17]
	v_pk_fma_f32 v[120:121], v[120:121], v[56:57], v[18:19]
	v_pk_mul_f32 v[16:17], v[50:51], v[34:35]
	v_pk_mul_f32 v[18:19], v[48:49], v[32:33]
	v_pk_fma_f32 v[126:127], v[126:127], v[52:53], v[16:17]
	v_pk_fma_f32 v[124:125], v[124:125], v[56:57], v[18:19]
	v_pk_mul_f32 v[16:17], v[50:51], v[38:39]
	v_pk_mul_f32 v[18:19], v[48:49], v[36:37]
	v_pk_fma_f32 v[130:131], v[130:131], v[52:53], v[16:17]
	v_pk_fma_f32 v[128:129], v[128:129], v[56:57], v[18:19]
	v_pk_mul_f32 v[16:17], v[50:51], v[42:43]
	v_pk_mul_f32 v[18:19], v[48:49], v[40:41]
	v_pk_fma_f32 v[134:135], v[134:135], v[52:53], v[16:17]
	v_pk_fma_f32 v[132:133], v[132:133], v[56:57], v[18:19]
	v_pk_mul_f32 v[16:17], v[50:51], v[46:47]
	v_pk_mul_f32 v[18:19], v[48:49], v[44:45]
	v_pk_fma_f32 v[138:139], v[138:139], v[52:53], v[16:17]
	v_pk_fma_f32 v[136:137], v[136:137], v[56:57], v[18:19]
	s_cmpk_eq_i32 s94, 0x800
	s_mov_b32 s95, s94
	s_waitcnt vmcnt(11)
	v_mov_b32_e32 v68, v203
	s_waitcnt vmcnt(8)
	v_mov_b32_e32 v70, v204
	s_waitcnt vmcnt(5)
	v_mov_b32_e32 v33, v206
	v_mov_b32_e32 v64, v194
	v_mov_b32_e32 v65, v195
	v_mov_b32_e32 v66, v199
	v_mov_b32_e32 v67, v201
	s_waitcnt vmcnt(4)
	v_mov_b32_e32 v69, v205
	v_mov_b32_e32 v54, v197
	v_mov_b32_e32 v55, v200
	v_mov_b32_e32 v76, v202
	v_mov_b32_e32 v71, v191
	v_mov_b32_e32 v72, v192
	v_mov_b32_e32 v73, v193
	v_mov_b32_e32 v74, v196
	v_mov_b32_e32 v75, v198
	s_cbranch_scc1 .LBB0_1397
	.p2alignl 6, 3212836864

; #define PG8_STAGE(bufoff, gbase, voff) do { _Pragma("unroll") for (int _i = 0; _i < 2; ++_i) \
;         __builtin_amdgcn_global_load_lds((const unsigned*)((const char*)(gbase) + (voff)[_i]), (PG8_LAS unsigned*)(lds + (bufoff) + ldsw + _i * 8192), 16, 0, 0); } while (0)
; #define PG8_LDA(dst, b, h) do { _Pragma("unroll") for (int m = 0; m < 4; ++m) _Pragma("unroll") for (int k = 0; k < 2; ++k) dst[m][k] = *(const PG8_LAS bf16x8*)(lds + PG8_SA(b, h) + aoff + m * 2048 + k * 1024); } while (0)
; #define PG8_LDB(dst, b, h) do { _Pragma("unroll") for (int n = 0; n < 2; ++n) _Pragma("unroll") for (int k = 0; k < 2; ++k) dst[n][k] = *(const PG8_LAS bf16x8*)(lds + PG8_SB(b, h) + boff + n * 2048 + k * 1024); } while (0)
; #define PG8_MMA(ai, bj, At, Bt) do { __builtin_amdgcn_s_setprio(1); _Pragma("unroll") for (int m = 0; m < 4; ++m) _Pragma("unroll") for (int n = 0; n < 2; ++n) _Pragma("unroll") for (int k = 0; k < 2; ++k) \
;         acc[ai][bj][m][n] = __builtin_amdgcn_mfma_f32_16x16x32_bf16(Bt[n][k], At[m][k], acc[ai][bj][m][n], 0, 0, 0); __builtin_amdgcn_s_setprio(0); } while (0)
; template <class Epi, class Sched, bool ALIGN_EPI = false, bool SP2 = false>
; __device__ __forceinline__ void gemm_phase(PG8_LAS unsigned char* lds, const Gemm g, const Sched& S, const Epi& E) {
;     ...
;         const bool has_next = S.next(ui + 1, nxt);
;         const char* nA = has_next ? (const char*)g.A + (size_t)nxt.pm * tstep + (size_t)nxt.pn * g.a_gs : cA; const char* nB = has_next ? (const char*)g.Bt + (size_t)nxt.pn * tstep : cB;
;         for (int t = 0; t < nt; t += 2) {
;             const bool last = (t == nt - 2);
;             const char* a1 = cA + (size_t)(t + 1) * kstep;
;             const char* a2 = last ? nA : cA + (size_t)(t + 2) * kstep; const char* b2 = last ? nB : cB + (size_t)(t + 2) * kstep;
;             const char* a3 = a2 + kstep; const char* b3 = b2 + kstep;
;             if (last && has_next) S.a_ready(nxt);
;             if constexpr (SP2) {
;             PG8_LDB(B0, 0, 0); PG8_LDB(B1, 0, 1); PG8_SCHED; PG8_LDA(At, 0, 0); PG8_STAGE(PG8_SA(1, 1), a1 + hstep, voffA);
;             PG8_WAIT_V(8); PG8_WAIT_L(0); PG8_BAR; PG8_MMA(0, 0, At, B0); PG8_MMA(0, 1, At, B1); PG8_BAR; PG8_SCHED;
;             PG8_LDA(At, 0, 1); PG8_STAGE(PG8_SB(0, 0), b2, voffB); PG8_STAGE(PG8_SB(0, 1), b2 + hstep, voffB); PG8_STAGE(PG8_SA(0, 0), a2, voffA);
.LBB0_1640:
	s_add_u32 s0, s0, 0x80
	s_addc_u32 s1, s1, 0
	s_add_u32 s44, s38, 0x100
	s_addc_u32 s45, s39, 0
	s_mov_b32 s38, 0
	s_add_i32 s78, s38, 2
	s_add_u32 s79, s0, 0x80
	s_addc_u32 s39, s1, 0
	s_add_i32 s93, 0, 0x10000
	s_cmp_eq_u32 s75, s38
	s_cselect_b32 s39, s63, s39
	s_cselect_b32 s38, s62, s79
	s_cselect_b32 s95, s65, s45
	s_cselect_b32 s94, s64, s44
	s_add_i32 s79, 0, 0x14000
	v_add_u32_e32 v68, s93, v218
	v_add_u32_e32 v156, s79, v218
	ds_read_b128 v[56:59], v68
	ds_read_b128 v[60:63], v68 offset:1024
	ds_read_b128 v[64:67], v68 offset:2048
	ds_read_b128 v[68:71], v68 offset:3072
	ds_read_b128 v[144:147], v156
	ds_read_b128 v[148:151], v156 offset:1024
	ds_read_b128 v[152:155], v156 offset:2048
	ds_read_b128 v[156:159], v156 offset:3072
	v_lshl_add_u64 v[172:173], s[0:1], 0, v[186:187]
	s_add_i32 m0, s9, 0xc000
	ds_read_b128 v[160:163], v220
	ds_read_b128 v[164:167], v220 offset:1024
	ds_read_b128 v[168:171], v220 offset:2048
	ds_read_b128 v[176:179], v220 offset:3072
	ds_read_b128 v[190:193], v220 offset:4096
	ds_read_b128 v[194:197], v220 offset:5120
	ds_read_b128 v[198:201], v220 offset:6144
	ds_read_b128 v[202:205], v220 offset:7168
	global_load_lds_dwordx4 v[172:173], off
	v_lshl_add_u64 v[172:173], s[0:1], 0, v[188:189]
	s_add_i32 m0, s9, 0xe000
	s_nop 0
	global_load_lds_dwordx4 v[172:173], off
	s_waitcnt vmcnt(8)
	s_waitcnt lgkmcnt(0)
	s_setprio 1
	s_barrier
	v_mfma_f32_16x16x32_bf16 v[140:143], v[56:59], v[160:163], 0
	v_mfma_f32_16x16x32_bf16 v[136:139], v[64:67], v[160:163], 0
	v_mfma_f32_16x16x32_bf16 v[124:127], v[56:59], v[168:171], 0
	v_mfma_f32_16x16x32_bf16 v[120:123], v[64:67], v[168:171], 0
	v_mfma_f32_16x16x32_bf16 v[108:111], v[56:59], v[190:193], 0
	v_mfma_f32_16x16x32_bf16 v[104:107], v[64:67], v[190:193], 0
	v_mfma_f32_16x16x32_bf16 v[92:95], v[56:59], v[198:201], 0
	v_mfma_f32_16x16x32_bf16 v[88:91], v[64:67], v[198:201], 0
	v_mfma_f32_16x16x32_bf16 v[140:143], v[60:63], v[164:167], v[140:143]
	v_mfma_f32_16x16x32_bf16 v[136:139], v[68:71], v[164:167], v[136:139]
	v_mfma_f32_16x16x32_bf16 v[124:127], v[60:63], v[176:179], v[124:127]
	v_mfma_f32_16x16x32_bf16 v[120:123], v[68:71], v[176:179], v[120:123]
	v_mfma_f32_16x16x32_bf16 v[108:111], v[60:63], v[194:197], v[108:111]
	v_mfma_f32_16x16x32_bf16 v[104:107], v[68:71], v[194:197], v[104:107]
	v_mfma_f32_16x16x32_bf16 v[92:95], v[60:63], v[202:205], v[92:95]
	v_mfma_f32_16x16x32_bf16 v[88:91], v[68:71], v[202:205], v[88:91]
	v_mfma_f32_16x16x32_bf16 v[132:135], v[144:147], v[160:163], 0
	v_mfma_f32_16x16x32_bf16 v[128:131], v[152:155], v[160:163], 0
	v_mfma_f32_16x16x32_bf16 v[116:119], v[144:147], v[168:171], 0
	v_mfma_f32_16x16x32_bf16 v[112:115], v[152:155], v[168:171], 0
	v_mfma_f32_16x16x32_bf16 v[100:103], v[144:147], v[190:193], 0
	v_mfma_f32_16x16x32_bf16 v[96:99], v[152:155], v[190:193], 0
	v_mfma_f32_16x16x32_bf16 v[84:87], v[144:147], v[198:201], 0
	v_mfma_f32_16x16x32_bf16 v[80:83], v[152:155], v[198:201], 0
	v_mfma_f32_16x16x32_bf16 v[132:135], v[148:151], v[164:167], v[132:135]
	v_mfma_f32_16x16x32_bf16 v[128:131], v[156:159], v[164:167], v[128:131]
	v_mfma_f32_16x16x32_bf16 v[116:119], v[148:151], v[176:179], v[116:119]
	v_mfma_f32_16x16x32_bf16 v[112:115], v[156:159], v[176:179], v[112:115]
	v_mfma_f32_16x16x32_bf16 v[100:103], v[148:151], v[194:197], v[100:103]
	v_mfma_f32_16x16x32_bf16 v[96:99], v[156:159], v[194:197], v[96:99]
	v_mfma_f32_16x16x32_bf16 v[84:87], v[148:151], v[202:205], v[84:87]
	v_mfma_f32_16x16x32_bf16 v[80:83], v[156:159], v[202:205], v[80:83]
	s_barrier
	s_setprio 0
	s_add_i32 s93, s93, s8
	v_lshl_add_u64 v[172:173], s[94:95], 0, v[174:175]
	s_mov_b32 m0, s93
	ds_read_b128 v[160:163], v220 offset:16384
	ds_read_b128 v[164:167], v220 offset:17408
	ds_read_b128 v[168:171], v220 offset:18432
	ds_read_b128 v[176:179], v220 offset:19456
	ds_read_b128 v[190:193], v220 offset:20480
	ds_read_b128 v[194:197], v220 offset:21504
	ds_read_b128 v[198:201], v220 offset:22528
	ds_read_b128 v[202:205], v220 offset:23552
	global_load_lds_dwordx4 v[172:173], off
	s_add_i32 m0, s93, 0x2000
	v_lshl_add_u64 v[206:207], s[94:95], 0, v[180:181]
	s_add_u32 s94, s94, s50
	s_addc_u32 s95, s95, 0
	s_add_i32 s79, s79, s8
	global_load_lds_dwordx4 v[206:207], off
	v_lshl_add_u64 v[208:209], s[94:95], 0, v[174:175]
	s_mov_b32 m0, s79
	v_lshl_add_u64 v[222:223], s[94:95], 0, v[180:181]
	global_load_lds_dwordx4 v[208:209], off
	s_add_i32 m0, s79, 0x2000
	v_lshl_add_u64 v[224:225], s[38:39], 0, v[184:185]
	global_load_lds_dwordx4 v[222:223], off
	s_mov_b32 m0, s9
	v_lshl_add_u64 v[226:227], s[38:39], 0, v[182:183]
	global_load_lds_dwordx4 v[224:225], off
	s_mov_b32 m0, s67
	s_nop 0
	global_load_lds_dwordx4 v[226:227], off
	s_waitcnt vmcnt(8)
	s_waitcnt lgkmcnt(0)
	s_setprio 1
	s_barrier
; #define PG8_STAGE(bufoff, gbase, voff) do { _Pragma("unroll") for (int _i = 0; _i < 2; ++_i) \
;         __builtin_amdgcn_global_load_lds((const unsigned*)((const char*)(gbase) + (voff)[_i]), (PG8_LAS unsigned*)(lds + (bufoff) + ldsw + _i * 8192), 16, 0, 0); } while (0)
; #define PG8_LDA(dst, b, h) do { _Pragma("unroll") for (int m = 0; m < 4; ++m) _Pragma("unroll") for (int k = 0; k < 2; ++k) dst[m][k] = *(const PG8_LAS bf16x8*)(lds + PG8_SA(b, h) + aoff + m * 2048 + k * 1024); } while (0)
; #define PG8_LDB(dst, b, h) do { _Pragma("unroll") for (int n = 0; n < 2; ++n) _Pragma("unroll") for (int k = 0; k < 2; ++k) dst[n][k] = *(const PG8_LAS bf16x8*)(lds + PG8_SB(b, h) + boff + n * 2048 + k * 1024); } while (0)
; #define PG8_MMA(ai, bj, At, Bt) do { __builtin_amdgcn_s_setprio(1); _Pragma("unroll") for (int m = 0; m < 4; ++m) _Pragma("unroll") for (int n = 0; n < 2; ++n) _Pragma("unroll") for (int k = 0; k < 2; ++k) \
;         acc[ai][bj][m][n] = __builtin_amdgcn_mfma_f32_16x16x32_bf16(Bt[n][k], At[m][k], acc[ai][bj][m][n], 0, 0, 0); __builtin_amdgcn_s_setprio(0); } while (0)
; #define PG8_WAIT_V(n) asm volatile("s_waitcnt vmcnt(" #n ")" ::: "memory")
; template <class Epi, class Sched, bool ALIGN_EPI = false, bool SP2 = false>
; __device__ __forceinline__ void gemm_phase(PG8_LAS unsigned char* lds, const Gemm g, const Sched& S, const Epi& E) {
;     ...
;             PG8_LDB(B0, 0, 0); PG8_LDB(B1, 0, 1); PG8_SCHED; PG8_LDA(At, 0, 0); PG8_STAGE(PG8_SA(1, 1), a1 + hstep, voffA);
;             PG8_WAIT_V(8); PG8_WAIT_L(0); PG8_BAR; PG8_MMA(0, 0, At, B0); PG8_MMA(0, 1, At, B1); PG8_BAR; PG8_SCHED;
;             PG8_LDA(At, 0, 1); PG8_STAGE(PG8_SB(0, 0), b2, voffB); PG8_STAGE(PG8_SB(0, 1), b2 + hstep, voffB); PG8_STAGE(PG8_SA(0, 0), a2, voffA);
;             PG8_WAIT_V(8); PG8_WAIT_L(0); PG8_BAR; PG8_MMA(1, 0, At, B0); PG8_MMA(1, 1, At, B1); PG8_BAR; PG8_SCHED;
;             PG8_LDB(B0, 1, 0); PG8_LDB(B1, 1, 1); PG8_SCHED; PG8_LDA(At, 1, 0); PG8_STAGE(PG8_SA(0, 1), a2 + hstep, voffA);
;             PG8_WAIT_V(8); PG8_WAIT_L(0); PG8_BAR; PG8_MMA(0, 0, At, B0); PG8_MMA(0, 1, At, B1); PG8_BAR; PG8_SCHED;
;             PG8_LDA(At, 1, 1); PG8_STAGE(PG8_SB(1, 0), b3, voffB); PG8_STAGE(PG8_SB(1, 1), b3 + hstep, voffB); PG8_STAGE(PG8_SA(1, 0), a3, voffA);
;             PG8_WAIT_V(8); PG8_WAIT_L(0); PG8_BAR; PG8_MMA(1, 0, At, B0); PG8_MMA(1, 1, At, B1); PG8_BAR; PG8_SCHED;
	v_mfma_f32_16x16x32_bf16 v[76:79], v[56:59], v[160:163], 0
	v_mfma_f32_16x16x32_bf16 v[72:75], v[64:67], v[160:163], 0
	v_mfma_f32_16x16x32_bf16 v[44:47], v[56:59], v[168:171], 0
	v_mfma_f32_16x16x32_bf16 v[40:43], v[64:67], v[168:171], 0
	v_mfma_f32_16x16x32_bf16 v[28:31], v[56:59], v[190:193], 0
	v_mfma_f32_16x16x32_bf16 v[24:27], v[64:67], v[190:193], 0
	v_mfma_f32_16x16x32_bf16 v[12:15], v[56:59], v[198:201], 0
	v_mfma_f32_16x16x32_bf16 v[8:11], v[64:67], v[198:201], 0
	v_mfma_f32_16x16x32_bf16 v[76:79], v[60:63], v[164:167], v[76:79]
	v_mfma_f32_16x16x32_bf16 v[72:75], v[68:71], v[164:167], v[72:75]
	v_mfma_f32_16x16x32_bf16 v[44:47], v[60:63], v[176:179], v[44:47]
	v_mfma_f32_16x16x32_bf16 v[40:43], v[68:71], v[176:179], v[40:43]
	v_mfma_f32_16x16x32_bf16 v[28:31], v[60:63], v[194:197], v[28:31]
	v_mfma_f32_16x16x32_bf16 v[24:27], v[68:71], v[194:197], v[24:27]
	v_mfma_f32_16x16x32_bf16 v[12:15], v[60:63], v[202:205], v[12:15]
	v_mfma_f32_16x16x32_bf16 v[8:11], v[68:71], v[202:205], v[8:11]
	v_mfma_f32_16x16x32_bf16 v[52:55], v[144:147], v[160:163], 0
	v_mfma_f32_16x16x32_bf16 v[48:51], v[152:155], v[160:163], 0
	v_mfma_f32_16x16x32_bf16 v[36:39], v[144:147], v[168:171], 0
	v_mfma_f32_16x16x32_bf16 v[32:35], v[152:155], v[168:171], 0
	v_mfma_f32_16x16x32_bf16 v[20:23], v[144:147], v[190:193], 0
	v_mfma_f32_16x16x32_bf16 v[16:19], v[152:155], v[190:193], 0
	v_mfma_f32_16x16x32_bf16 v[4:7], v[144:147], v[198:201], 0
	v_mfma_f32_16x16x32_bf16 v[0:3], v[152:155], v[198:201], 0
	v_mfma_f32_16x16x32_bf16 v[52:55], v[148:151], v[164:167], v[52:55]
	v_mfma_f32_16x16x32_bf16 v[48:51], v[156:159], v[164:167], v[48:51]
	v_mfma_f32_16x16x32_bf16 v[36:39], v[148:151], v[176:179], v[36:39]
	v_mfma_f32_16x16x32_bf16 v[32:35], v[156:159], v[176:179], v[32:35]
	v_mfma_f32_16x16x32_bf16 v[20:23], v[148:151], v[194:197], v[20:23]
	v_mfma_f32_16x16x32_bf16 v[16:19], v[156:159], v[194:197], v[16:19]
	v_mfma_f32_16x16x32_bf16 v[4:7], v[148:151], v[202:205], v[4:7]
	v_mfma_f32_16x16x32_bf16 v[0:3], v[156:159], v[202:205], v[0:3]
	s_barrier
	s_setprio 0
	s_add_i32 s79, 0, 0x18000
	s_add_i32 s93, 0, 0x1c000
	v_add_u32_e32 v68, s79, v218
	v_add_u32_e32 v156, s93, v218
	ds_read_b128 v[56:59], v68
	ds_read_b128 v[60:63], v68 offset:1024
	ds_read_b128 v[64:67], v68 offset:2048
	ds_read_b128 v[68:71], v68 offset:3072
	ds_read_b128 v[144:147], v156
	ds_read_b128 v[148:151], v156 offset:1024
	ds_read_b128 v[152:155], v156 offset:2048
	ds_read_b128 v[156:159], v156 offset:3072
	s_add_u32 s38, s38, s50
	s_addc_u32 s39, s39, 0
	s_mov_b32 m0, s68
	v_lshl_add_u64 v[228:229], s[38:39], 0, v[184:185]
	ds_read_b128 v[160:163], v220 offset:32768
	ds_read_b128 v[164:167], v220 offset:33792
	ds_read_b128 v[168:171], v220 offset:34816
	ds_read_b128 v[176:179], v220 offset:35840
	ds_read_b128 v[190:193], v220 offset:36864
	ds_read_b128 v[194:197], v220 offset:37888
	ds_read_b128 v[198:201], v220 offset:38912
	ds_read_b128 v[202:205], v220 offset:39936
	global_load_lds_dwordx4 v[228:229], off
	v_lshl_add_u64 v[228:229], s[38:39], 0, v[182:183]
	s_mov_b32 m0, s69
	s_nop 0
	global_load_lds_dwordx4 v[228:229], off
	s_waitcnt vmcnt(8)
	s_waitcnt lgkmcnt(0)
	s_setprio 1
	s_barrier
	v_mfma_f32_16x16x32_bf16 v[140:143], v[56:59], v[160:163], v[140:143]
	v_mfma_f32_16x16x32_bf16 v[136:139], v[64:67], v[160:163], v[136:139]
	v_mfma_f32_16x16x32_bf16 v[124:127], v[56:59], v[168:171], v[124:127]
	v_mfma_f32_16x16x32_bf16 v[120:123], v[64:67], v[168:171], v[120:123]
	v_mfma_f32_16x16x32_bf16 v[108:111], v[56:59], v[190:193], v[108:111]
	v_mfma_f32_16x16x32_bf16 v[104:107], v[64:67], v[190:193], v[104:107]
	v_mfma_f32_16x16x32_bf16 v[92:95], v[56:59], v[198:201], v[92:95]
	v_mfma_f32_16x16x32_bf16 v[88:91], v[64:67], v[198:201], v[88:91]
	v_mfma_f32_16x16x32_bf16 v[140:143], v[60:63], v[164:167], v[140:143]
	v_mfma_f32_16x16x32_bf16 v[136:139], v[68:71], v[164:167], v[136:139]
	v_mfma_f32_16x16x32_bf16 v[124:127], v[60:63], v[176:179], v[124:127]
	v_mfma_f32_16x16x32_bf16 v[120:123], v[68:71], v[176:179], v[120:123]
	v_mfma_f32_16x16x32_bf16 v[108:111], v[60:63], v[194:197], v[108:111]
	v_mfma_f32_16x16x32_bf16 v[104:107], v[68:71], v[194:197], v[104:107]
	v_mfma_f32_16x16x32_bf16 v[92:95], v[60:63], v[202:205], v[92:95]
	v_mfma_f32_16x16x32_bf16 v[88:91], v[68:71], v[202:205], v[88:91]
	v_mfma_f32_16x16x32_bf16 v[132:135], v[144:147], v[160:163], v[132:135]
	v_mfma_f32_16x16x32_bf16 v[128:131], v[152:155], v[160:163], v[128:131]
	v_mfma_f32_16x16x32_bf16 v[116:119], v[144:147], v[168:171], v[116:119]
	v_mfma_f32_16x16x32_bf16 v[112:115], v[152:155], v[168:171], v[112:115]
	v_mfma_f32_16x16x32_bf16 v[100:103], v[144:147], v[190:193], v[100:103]
	v_mfma_f32_16x16x32_bf16 v[96:99], v[152:155], v[190:193], v[96:99]
	v_mfma_f32_16x16x32_bf16 v[84:87], v[144:147], v[198:201], v[84:87]
	v_mfma_f32_16x16x32_bf16 v[80:83], v[152:155], v[198:201], v[80:83]
	v_mfma_f32_16x16x32_bf16 v[132:135], v[148:151], v[164:167], v[132:135]
	v_mfma_f32_16x16x32_bf16 v[128:131], v[156:159], v[164:167], v[128:131]
	v_mfma_f32_16x16x32_bf16 v[116:119], v[148:151], v[176:179], v[116:119]
	v_mfma_f32_16x16x32_bf16 v[112:115], v[156:159], v[176:179], v[112:115]
	v_mfma_f32_16x16x32_bf16 v[100:103], v[148:151], v[194:197], v[100:103]
	v_mfma_f32_16x16x32_bf16 v[96:99], v[156:159], v[194:197], v[96:99]
	v_mfma_f32_16x16x32_bf16 v[84:87], v[148:151], v[202:205], v[84:87]
	v_mfma_f32_16x16x32_bf16 v[80:83], v[156:159], v[202:205], v[80:83]
	s_barrier
; #define PG8_STAGE(bufoff, gbase, voff) do { _Pragma("unroll") for (int _i = 0; _i < 2; ++_i) \
;         __builtin_amdgcn_global_load_lds((const unsigned*)((const char*)(gbase) + (voff)[_i]), (PG8_LAS unsigned*)(lds + (bufoff) + ldsw + _i * 8192), 16, 0, 0); } while (0)
; #define PG8_LDA(dst, b, h) do { _Pragma("unroll") for (int m = 0; m < 4; ++m) _Pragma("unroll") for (int k = 0; k < 2; ++k) dst[m][k] = *(const PG8_LAS bf16x8*)(lds + PG8_SA(b, h) + aoff + m * 2048 + k * 1024); } while (0)
; #define PG8_LDB(dst, b, h) do { _Pragma("unroll") for (int n = 0; n < 2; ++n) _Pragma("unroll") for (int k = 0; k < 2; ++k) dst[n][k] = *(const PG8_LAS bf16x8*)(lds + PG8_SB(b, h) + boff + n * 2048 + k * 1024); } while (0)
; template <class Epi, class Sched, bool ALIGN_EPI = false, bool SP2 = false>
; __device__ __forceinline__ void gemm_phase(PG8_LAS unsigned char* lds, const Gemm g, const Sched& S, const Epi& E) {
;     ...
;         for (int t = 0; t < nt; t += 2) {
;             const bool last = (t == nt - 2);
;             const char* a1 = cA + (size_t)(t + 1) * kstep;
;             const char* a2 = last ? nA : cA + (size_t)(t + 2) * kstep; const char* b2 = last ? nB : cB + (size_t)(t + 2) * kstep;
;             const char* a3 = a2 + kstep; const char* b3 = b2 + kstep;
;             if (last && has_next) S.a_ready(nxt);
;             if constexpr (SP2) {
;             PG8_LDB(B0, 0, 0); PG8_LDB(B1, 0, 1); PG8_SCHED; PG8_LDA(At, 0, 0); PG8_STAGE(PG8_SA(1, 1), a1 + hstep, voffA);
;             PG8_WAIT_V(8); PG8_WAIT_L(0); PG8_BAR; PG8_MMA(0, 0, At, B0); PG8_MMA(0, 1, At, B1); PG8_BAR; PG8_SCHED;
;             PG8_LDA(At, 0, 1); PG8_STAGE(PG8_SB(0, 0), b2, voffB); PG8_STAGE(PG8_SB(0, 1), b2 + hstep, voffB); PG8_STAGE(PG8_SA(0, 0), a2, voffA);
;             PG8_WAIT_V(8); PG8_WAIT_L(0); PG8_BAR; PG8_MMA(1, 0, At, B0); PG8_MMA(1, 1, At, B1); PG8_BAR; PG8_SCHED;
;             PG8_LDB(B0, 1, 0); PG8_LDB(B1, 1, 1); PG8_SCHED; PG8_LDA(At, 1, 0); PG8_STAGE(PG8_SA(0, 1), a2 + hstep, voffA);
;             PG8_WAIT_V(8); PG8_WAIT_L(0); PG8_BAR; PG8_MMA(0, 0, At, B0); PG8_MMA(0, 1, At, B1); PG8_BAR; PG8_SCHED;
;             PG8_LDA(At, 1, 1); PG8_STAGE(PG8_SB(1, 0), b3, voffB); PG8_STAGE(PG8_SB(1, 1), b3 + hstep, voffB); PG8_STAGE(PG8_SA(1, 0), a3, voffA);
;             PG8_WAIT_V(8); PG8_WAIT_L(0); PG8_BAR; PG8_MMA(1, 0, At, B0); PG8_MMA(1, 1, At, B1); PG8_BAR; PG8_SCHED;
	s_setprio 0
	s_add_i32 s38, s79, s8
	v_lshl_add_u64 v[172:173], v[172:173], 0, s[4:5]
	s_mov_b32 m0, s38
	ds_read_b128 v[160:163], v220 offset:49152
	ds_read_b128 v[164:167], v220 offset:50176
	ds_read_b128 v[168:171], v220 offset:51200
	ds_read_b128 v[176:179], v220 offset:52224
	ds_read_b128 v[190:193], v220 offset:53248
	ds_read_b128 v[194:197], v220 offset:54272
	ds_read_b128 v[198:201], v220 offset:55296
	ds_read_b128 v[202:205], v220 offset:56320
	global_load_lds_dwordx4 v[172:173], off
	v_lshl_add_u64 v[172:173], v[206:207], 0, s[4:5]
	s_add_i32 m0, s38, 0x2000
	s_add_i32 s38, s93, s8
	global_load_lds_dwordx4 v[172:173], off
	v_lshl_add_u64 v[172:173], v[208:209], 0, s[4:5]
	s_mov_b32 m0, s38
	s_nop 0
	global_load_lds_dwordx4 v[172:173], off
	v_lshl_add_u64 v[172:173], v[222:223], 0, s[4:5]
	s_add_i32 m0, s38, 0x2000
	s_nop 0
	global_load_lds_dwordx4 v[172:173], off
	v_lshl_add_u64 v[172:173], v[224:225], 0, s[4:5]
	s_mov_b32 m0, s73
	s_nop 0
	global_load_lds_dwordx4 v[172:173], off
	v_lshl_add_u64 v[172:173], v[226:227], 0, s[4:5]
	s_mov_b32 m0, s74
	s_nop 0
	global_load_lds_dwordx4 v[172:173], off
	s_waitcnt vmcnt(8)
	s_waitcnt lgkmcnt(0)
	s_setprio 1
	s_barrier
	v_mfma_f32_16x16x32_bf16 v[76:79], v[56:59], v[160:163], v[76:79]
	v_mfma_f32_16x16x32_bf16 v[72:75], v[64:67], v[160:163], v[72:75]
	v_mfma_f32_16x16x32_bf16 v[44:47], v[56:59], v[168:171], v[44:47]
	v_mfma_f32_16x16x32_bf16 v[40:43], v[64:67], v[168:171], v[40:43]
	v_mfma_f32_16x16x32_bf16 v[28:31], v[56:59], v[190:193], v[28:31]
	v_mfma_f32_16x16x32_bf16 v[24:27], v[64:67], v[190:193], v[24:27]
	v_mfma_f32_16x16x32_bf16 v[12:15], v[56:59], v[198:201], v[12:15]
	v_mfma_f32_16x16x32_bf16 v[8:11], v[64:67], v[198:201], v[8:11]
	v_mfma_f32_16x16x32_bf16 v[76:79], v[60:63], v[164:167], v[76:79]
	v_mfma_f32_16x16x32_bf16 v[72:75], v[68:71], v[164:167], v[72:75]
	v_mfma_f32_16x16x32_bf16 v[44:47], v[60:63], v[176:179], v[44:47]
	v_mfma_f32_16x16x32_bf16 v[40:43], v[68:71], v[176:179], v[40:43]
	v_mfma_f32_16x16x32_bf16 v[28:31], v[60:63], v[194:197], v[28:31]
	v_mfma_f32_16x16x32_bf16 v[24:27], v[68:71], v[194:197], v[24:27]
	v_mfma_f32_16x16x32_bf16 v[12:15], v[60:63], v[202:205], v[12:15]
	v_mfma_f32_16x16x32_bf16 v[8:11], v[68:71], v[202:205], v[8:11]
	v_mfma_f32_16x16x32_bf16 v[52:55], v[144:147], v[160:163], v[52:55]
	v_mfma_f32_16x16x32_bf16 v[48:51], v[152:155], v[160:163], v[48:51]
	v_mfma_f32_16x16x32_bf16 v[36:39], v[144:147], v[168:171], v[36:39]
	v_mfma_f32_16x16x32_bf16 v[32:35], v[152:155], v[168:171], v[32:35]
	v_mfma_f32_16x16x32_bf16 v[20:23], v[144:147], v[190:193], v[20:23]
	v_mfma_f32_16x16x32_bf16 v[16:19], v[152:155], v[190:193], v[16:19]
	v_mfma_f32_16x16x32_bf16 v[4:7], v[144:147], v[198:201], v[4:7]
	v_mfma_f32_16x16x32_bf16 v[0:3], v[152:155], v[198:201], v[0:3]
	v_mfma_f32_16x16x32_bf16 v[52:55], v[148:151], v[164:167], v[52:55]
	v_mfma_f32_16x16x32_bf16 v[48:51], v[156:159], v[164:167], v[48:51]
	v_mfma_f32_16x16x32_bf16 v[36:39], v[148:151], v[176:179], v[36:39]
	v_mfma_f32_16x16x32_bf16 v[32:35], v[156:159], v[176:179], v[32:35]
	v_mfma_f32_16x16x32_bf16 v[20:23], v[148:151], v[194:197], v[20:23]
	v_mfma_f32_16x16x32_bf16 v[16:19], v[156:159], v[194:197], v[16:19]
	v_mfma_f32_16x16x32_bf16 v[4:7], v[148:151], v[202:205], v[4:7]
	v_mfma_f32_16x16x32_bf16 v[0:3], v[156:159], v[202:205], v[0:3]
	s_barrier
	s_setprio 0
	s_add_u32 s0, s0, 0x100
	s_addc_u32 s1, s1, 0
	s_add_u32 s44, s44, 0x100
	s_addc_u32 s45, s45, 0
	s_cmp_ge_u32 s78, s72
	s_mov_b32 s38, s78
	s_cbranch_scc0 .LBB0_1641
	.p2alignl 6, 3212836864

; #define PG8_STAGE(bufoff, gbase, voff) do { _Pragma("unroll") for (int _i = 0; _i < 2; ++_i) \
;         __builtin_amdgcn_global_load_lds((const unsigned*)((const char*)(gbase) + (voff)[_i]), (PG8_LAS unsigned*)(lds + (bufoff) + ldsw + _i * 8192), 16, 0, 0); } while (0)
; #define PG8_LDA(dst, b, h) do { _Pragma("unroll") for (int m = 0; m < 4; ++m) _Pragma("unroll") for (int k = 0; k < 2; ++k) dst[m][k] = *(const PG8_LAS bf16x8*)(lds + PG8_SA(b, h) + aoff + m * 2048 + k * 1024); } while (0)
; #define PG8_LDB(dst, b, h) do { _Pragma("unroll") for (int n = 0; n < 2; ++n) _Pragma("unroll") for (int k = 0; k < 2; ++k) dst[n][k] = *(const PG8_LAS bf16x8*)(lds + PG8_SB(b, h) + boff + n * 2048 + k * 1024); } while (0)
; #define PG8_WAIT_V(n) asm volatile("s_waitcnt vmcnt(" #n ")" ::: "memory")
; #define PG8_WAIT_L(n) asm volatile("s_waitcnt lgkmcnt(" #n ")" ::: "memory")
; #define PG8_BAR __builtin_amdgcn_s_barrier()
; #define PG8_SCHED __builtin_amdgcn_sched_barrier(0)
; template <class Epi, class Sched, bool ALIGN_EPI = false, bool SP2 = false>
; __device__ __forceinline__ void gemm_phase(PG8_LAS unsigned char* lds, const Gemm g, const Sched& S, const Epi& E) {
;     ...
;         const bool has_next = S.next(ui + 1, nxt);
;         const char* nA = has_next ? (const char*)g.A + (size_t)nxt.pm * tstep + (size_t)nxt.pn * g.a_gs : cA; const char* nB = has_next ? (const char*)g.Bt + (size_t)nxt.pn * tstep : cB;
;         for (int t = 0; t < nt; t += 2) {
;             const bool last = (t == nt - 2);
;             const char* a1 = cA + (size_t)(t + 1) * kstep;
;             const char* a2 = last ? nA : cA + (size_t)(t + 2) * kstep; const char* b2 = last ? nB : cB + (size_t)(t + 2) * kstep;
;             const char* a3 = a2 + kstep; const char* b3 = b2 + kstep;
;             if (last && has_next) S.a_ready(nxt);
;             if constexpr (SP2) {
;             PG8_LDB(B0, 0, 0); PG8_LDB(B1, 0, 1); PG8_SCHED; PG8_LDA(At, 0, 0); PG8_STAGE(PG8_SA(1, 1), a1 + hstep, voffA);
;             PG8_WAIT_V(8); PG8_WAIT_L(0); PG8_BAR; PG8_MMA(0, 0, At, B0); PG8_MMA(0, 1, At, B1); PG8_BAR; PG8_SCHED;
;             PG8_LDA(At, 0, 1); PG8_STAGE(PG8_SB(0, 0), b2, voffB); PG8_STAGE(PG8_SB(0, 1), b2 + hstep, voffB); PG8_STAGE(PG8_SA(0, 0), a2, voffA);
;             PG8_WAIT_V(8); PG8_WAIT_L(0); PG8_BAR; PG8_MMA(1, 0, At, B0); PG8_MMA(1, 1, At, B1); PG8_BAR; PG8_SCHED;
.LBB0_1751:
	s_ashr_i32 s51, s50, 31
	s_lshl_b64 s[52:53], s[50:51], 19
	s_add_u32 s52, s10, s52
	s_addc_u32 s53, s11, s53
	s_and_b64 s[54:55], s[42:43], exec
	s_cselect_b32 s51, s53, s1
	s_cselect_b32 s69, s52, s0
	s_ashr_i32 s49, s48, 31
	s_lshl_b64 s[54:55], s[48:49], 19
	s_add_u32 s54, s9, s54
	s_addc_u32 s55, s16, s55
	s_and_b64 s[56:57], s[42:43], exec
	s_cselect_b32 s49, s55, s39
	s_cselect_b32 s70, s54, s38
	s_add_u32 s0, s0, 0x40080
	s_addc_u32 s1, s1, 0
	s_add_u32 s71, s38, 0x100
	s_addc_u32 s72, s39, 0
	s_mov_b32 s73, -2
	s_add_u32 s38, s0, 0xfffc0080
	s_addc_u32 s39, s1, -1
	s_add_i32 s74, 0, 0x10000
	s_cmp_eq_u32 s73, 12
	s_cselect_b32 s57, s51, s39
	s_cselect_b32 s56, s69, s38
	v_add_u32_e32 v151, s74, v147
	s_cselect_b32 s39, s49, s72
	s_cselect_b32 s38, s70, s71
	s_add_i32 s76, 0, 0x14000
	ds_read_b128 v[138:141], v151
	ds_read_b128 v[142:145], v151 offset:1024
	ds_read_b128 v[152:155], v151 offset:2048
	ds_read_b128 v[156:159], v151 offset:3072
	v_add_u32_e32 v151, s76, v147
	ds_read_b128 v[160:163], v151
	ds_read_b128 v[164:167], v151 offset:1024
	ds_read_b128 v[168:171], v151 offset:2048
	ds_read_b128 v[176:179], v151 offset:3072
	v_lshl_add_u64 v[172:173], s[0:1], 0, v[134:135]
	s_add_i32 m0, s58, 0xc000
	ds_read_b128 v[180:183], v150
	ds_read_b128 v[184:187], v150 offset:1024
	ds_read_b128 v[188:191], v150 offset:2048
	ds_read_b128 v[192:195], v150 offset:3072
	ds_read_b128 v[196:199], v150 offset:4096
	ds_read_b128 v[200:203], v150 offset:5120
	ds_read_b128 v[204:207], v150 offset:6144
	ds_read_b128 v[218:221], v150 offset:7168
	global_load_lds_dwordx4 v[172:173], off
	v_lshl_add_u64 v[172:173], s[0:1], 0, v[136:137]
	s_add_i32 m0, s58, 0xe000
	s_nop 0
	global_load_lds_dwordx4 v[172:173], off
	s_waitcnt vmcnt(8)
	s_waitcnt lgkmcnt(0)
	s_setprio 1
	s_barrier
	v_mfma_f32_16x16x32_bf16 v[124:127], v[138:141], v[180:183], 0
	v_mfma_f32_16x16x32_bf16 v[120:123], v[152:155], v[180:183], 0
	v_mfma_f32_16x16x32_bf16 v[108:111], v[138:141], v[188:191], 0
	v_mfma_f32_16x16x32_bf16 v[104:107], v[152:155], v[188:191], 0
	v_mfma_f32_16x16x32_bf16 v[92:95], v[138:141], v[196:199], 0
	v_mfma_f32_16x16x32_bf16 v[88:91], v[152:155], v[196:199], 0
	v_mfma_f32_16x16x32_bf16 v[76:79], v[138:141], v[204:207], 0
	v_mfma_f32_16x16x32_bf16 v[72:75], v[152:155], v[204:207], 0
	v_mfma_f32_16x16x32_bf16 v[124:127], v[142:145], v[184:187], v[124:127]
	v_mfma_f32_16x16x32_bf16 v[120:123], v[156:159], v[184:187], v[120:123]
	v_mfma_f32_16x16x32_bf16 v[108:111], v[142:145], v[192:195], v[108:111]
	v_mfma_f32_16x16x32_bf16 v[104:107], v[156:159], v[192:195], v[104:107]
	v_mfma_f32_16x16x32_bf16 v[92:95], v[142:145], v[200:203], v[92:95]
	v_mfma_f32_16x16x32_bf16 v[88:91], v[156:159], v[200:203], v[88:91]
	v_mfma_f32_16x16x32_bf16 v[76:79], v[142:145], v[218:221], v[76:79]
	v_mfma_f32_16x16x32_bf16 v[72:75], v[156:159], v[218:221], v[72:75]
	v_mfma_f32_16x16x32_bf16 v[116:119], v[160:163], v[180:183], 0
	v_mfma_f32_16x16x32_bf16 v[112:115], v[168:171], v[180:183], 0
	v_mfma_f32_16x16x32_bf16 v[100:103], v[160:163], v[188:191], 0
	v_mfma_f32_16x16x32_bf16 v[96:99], v[168:171], v[188:191], 0
	v_mfma_f32_16x16x32_bf16 v[84:87], v[160:163], v[196:199], 0
	v_mfma_f32_16x16x32_bf16 v[80:83], v[168:171], v[196:199], 0
	v_mfma_f32_16x16x32_bf16 v[68:71], v[160:163], v[204:207], 0
	v_mfma_f32_16x16x32_bf16 v[64:67], v[168:171], v[204:207], 0
	v_mfma_f32_16x16x32_bf16 v[116:119], v[164:167], v[184:187], v[116:119]
	v_mfma_f32_16x16x32_bf16 v[112:115], v[176:179], v[184:187], v[112:115]
	v_mfma_f32_16x16x32_bf16 v[100:103], v[164:167], v[192:195], v[100:103]
	v_mfma_f32_16x16x32_bf16 v[96:99], v[176:179], v[192:195], v[96:99]
	v_mfma_f32_16x16x32_bf16 v[84:87], v[164:167], v[200:203], v[84:87]
	v_mfma_f32_16x16x32_bf16 v[80:83], v[176:179], v[200:203], v[80:83]
	v_mfma_f32_16x16x32_bf16 v[68:71], v[164:167], v[218:221], v[68:71]
	v_mfma_f32_16x16x32_bf16 v[64:67], v[176:179], v[218:221], v[64:67]
	s_barrier
	s_setprio 0
	s_add_i32 s74, s74, s8
	v_lshl_add_u64 v[172:173], s[38:39], 0, v[174:175]
	s_mov_b32 m0, s74
	ds_read_b128 v[180:183], v150 offset:16384
	ds_read_b128 v[184:187], v150 offset:17408
	ds_read_b128 v[188:191], v150 offset:18432
	ds_read_b128 v[192:195], v150 offset:19456
	ds_read_b128 v[196:199], v150 offset:20480
	ds_read_b128 v[200:203], v150 offset:21504
	ds_read_b128 v[204:207], v150 offset:22528
	ds_read_b128 v[218:221], v150 offset:23552
	global_load_lds_dwordx4 v[172:173], off
	s_add_i32 m0, s74, 0x2000
	s_add_u32 s74, s38, 0x40000
	v_lshl_add_u64 v[208:209], s[38:39], 0, v[128:129]
	s_addc_u32 s75, s39, 0
	s_add_i32 s76, s76, s8
	global_load_lds_dwordx4 v[208:209], off
	v_lshl_add_u64 v[222:223], s[74:75], 0, v[174:175]
	s_mov_b32 m0, s76
	v_lshl_add_u64 v[224:225], s[56:57], 0, v[130:131]
	global_load_lds_dwordx4 v[222:223], off
	v_lshl_add_u64 v[222:223], s[74:75], 0, v[128:129]
	s_add_i32 m0, s76, 0x2000
	s_nop 0
	global_load_lds_dwordx4 v[222:223], off
	v_lshl_add_u64 v[222:223], s[56:57], 0, v[132:133]
	s_mov_b32 m0, s58
	s_nop 0
	global_load_lds_dwordx4 v[222:223], off
	s_mov_b32 m0, s59
	s_nop 0
	global_load_lds_dwordx4 v[224:225], off
	s_waitcnt vmcnt(8)
	s_waitcnt lgkmcnt(0)
	s_setprio 1
	s_barrier
; #define PG8_STAGE(bufoff, gbase, voff) do { _Pragma("unroll") for (int _i = 0; _i < 2; ++_i) \
;         __builtin_amdgcn_global_load_lds((const unsigned*)((const char*)(gbase) + (voff)[_i]), (PG8_LAS unsigned*)(lds + (bufoff) + ldsw + _i * 8192), 16, 0, 0); } while (0)
; #define PG8_LDA(dst, b, h) do { _Pragma("unroll") for (int m = 0; m < 4; ++m) _Pragma("unroll") for (int k = 0; k < 2; ++k) dst[m][k] = *(const PG8_LAS bf16x8*)(lds + PG8_SA(b, h) + aoff + m * 2048 + k * 1024); } while (0)
; #define PG8_LDB(dst, b, h) do { _Pragma("unroll") for (int n = 0; n < 2; ++n) _Pragma("unroll") for (int k = 0; k < 2; ++k) dst[n][k] = *(const PG8_LAS bf16x8*)(lds + PG8_SB(b, h) + boff + n * 2048 + k * 1024); } while (0)
; #define PG8_MMA(ai, bj, At, Bt) do { __builtin_amdgcn_s_setprio(1); _Pragma("unroll") for (int m = 0; m < 4; ++m) _Pragma("unroll") for (int n = 0; n < 2; ++n) _Pragma("unroll") for (int k = 0; k < 2; ++k) \
;         acc[ai][bj][m][n] = __builtin_amdgcn_mfma_f32_16x16x32_bf16(Bt[n][k], At[m][k], acc[ai][bj][m][n], 0, 0, 0); __builtin_amdgcn_s_setprio(0); } while (0)
; #define PG8_WAIT_V(n) asm volatile("s_waitcnt vmcnt(" #n ")" ::: "memory")
; #define PG8_WAIT_L(n) asm volatile("s_waitcnt lgkmcnt(" #n ")" ::: "memory")
; #define PG8_BAR __builtin_amdgcn_s_barrier()
; #define PG8_SCHED __builtin_amdgcn_sched_barrier(0)
; template <class Epi, class Sched, bool ALIGN_EPI = false, bool SP2 = false>
; __device__ __forceinline__ void gemm_phase(PG8_LAS unsigned char* lds, const Gemm g, const Sched& S, const Epi& E) {
;     ...
;             PG8_WAIT_V(8); PG8_WAIT_L(0); PG8_BAR; PG8_MMA(1, 0, At, B0); PG8_MMA(1, 1, At, B1); PG8_BAR; PG8_SCHED;
;             PG8_LDB(B0, 1, 0); PG8_LDB(B1, 1, 1); PG8_SCHED; PG8_LDA(At, 1, 0); PG8_STAGE(PG8_SA(0, 1), a2 + hstep, voffA);
;             PG8_WAIT_V(8); PG8_WAIT_L(0); PG8_BAR; PG8_MMA(0, 0, At, B0); PG8_MMA(0, 1, At, B1); PG8_BAR; PG8_SCHED;
	v_mfma_f32_16x16x32_bf16 v[60:63], v[138:141], v[180:183], 0
	v_mfma_f32_16x16x32_bf16 v[56:59], v[152:155], v[180:183], 0
	v_mfma_f32_16x16x32_bf16 v[44:47], v[138:141], v[188:191], 0
	v_mfma_f32_16x16x32_bf16 v[40:43], v[152:155], v[188:191], 0
	v_mfma_f32_16x16x32_bf16 v[28:31], v[138:141], v[196:199], 0
	v_mfma_f32_16x16x32_bf16 v[24:27], v[152:155], v[196:199], 0
	v_mfma_f32_16x16x32_bf16 v[12:15], v[138:141], v[204:207], 0
	v_mfma_f32_16x16x32_bf16 v[8:11], v[152:155], v[204:207], 0
	v_mfma_f32_16x16x32_bf16 v[60:63], v[142:145], v[184:187], v[60:63]
	v_mfma_f32_16x16x32_bf16 v[56:59], v[156:159], v[184:187], v[56:59]
	v_mfma_f32_16x16x32_bf16 v[44:47], v[142:145], v[192:195], v[44:47]
	v_mfma_f32_16x16x32_bf16 v[40:43], v[156:159], v[192:195], v[40:43]
	v_mfma_f32_16x16x32_bf16 v[28:31], v[142:145], v[200:203], v[28:31]
	v_mfma_f32_16x16x32_bf16 v[24:27], v[156:159], v[200:203], v[24:27]
	v_mfma_f32_16x16x32_bf16 v[12:15], v[142:145], v[218:221], v[12:15]
	v_mfma_f32_16x16x32_bf16 v[8:11], v[156:159], v[218:221], v[8:11]
	v_mfma_f32_16x16x32_bf16 v[52:55], v[160:163], v[180:183], 0
	v_mfma_f32_16x16x32_bf16 v[48:51], v[168:171], v[180:183], 0
	v_mfma_f32_16x16x32_bf16 v[36:39], v[160:163], v[188:191], 0
	v_mfma_f32_16x16x32_bf16 v[32:35], v[168:171], v[188:191], 0
	v_mfma_f32_16x16x32_bf16 v[20:23], v[160:163], v[196:199], 0
	v_mfma_f32_16x16x32_bf16 v[16:19], v[168:171], v[196:199], 0
	v_mfma_f32_16x16x32_bf16 v[4:7], v[160:163], v[204:207], 0
	v_mfma_f32_16x16x32_bf16 v[0:3], v[168:171], v[204:207], 0
	v_mfma_f32_16x16x32_bf16 v[52:55], v[164:167], v[184:187], v[52:55]
	v_mfma_f32_16x16x32_bf16 v[48:51], v[176:179], v[184:187], v[48:51]
	v_mfma_f32_16x16x32_bf16 v[36:39], v[164:167], v[192:195], v[36:39]
	v_mfma_f32_16x16x32_bf16 v[32:35], v[176:179], v[192:195], v[32:35]
	v_mfma_f32_16x16x32_bf16 v[20:23], v[164:167], v[200:203], v[20:23]
	v_mfma_f32_16x16x32_bf16 v[16:19], v[176:179], v[200:203], v[16:19]
	v_mfma_f32_16x16x32_bf16 v[4:7], v[164:167], v[218:221], v[4:7]
	v_mfma_f32_16x16x32_bf16 v[0:3], v[176:179], v[218:221], v[0:3]
	s_barrier
	s_setprio 0
	s_add_i32 s74, 0, 0x18000
	v_add_u32_e32 v151, s74, v147
	s_add_i32 s75, 0, 0x1c000
	ds_read_b128 v[138:141], v151
	ds_read_b128 v[142:145], v151 offset:1024
	ds_read_b128 v[152:155], v151 offset:2048
	ds_read_b128 v[156:159], v151 offset:3072
	v_add_u32_e32 v151, s75, v147
	ds_read_b128 v[160:163], v151
	ds_read_b128 v[164:167], v151 offset:1024
	ds_read_b128 v[168:171], v151 offset:2048
	ds_read_b128 v[176:179], v151 offset:3072
	s_add_u32 s56, s56, 0x40000
	s_addc_u32 s57, s57, 0
	s_mov_b32 m0, s60
	v_lshl_add_u64 v[226:227], s[56:57], 0, v[132:133]
	ds_read_b128 v[180:183], v150 offset:32768
	ds_read_b128 v[184:187], v150 offset:33792
	ds_read_b128 v[188:191], v150 offset:34816
	ds_read_b128 v[192:195], v150 offset:35840
	ds_read_b128 v[196:199], v150 offset:36864
	ds_read_b128 v[200:203], v150 offset:37888
	ds_read_b128 v[204:207], v150 offset:38912
	ds_read_b128 v[218:221], v150 offset:39936
	global_load_lds_dwordx4 v[226:227], off
	v_lshl_add_u64 v[226:227], s[56:57], 0, v[130:131]
	s_mov_b32 m0, s61
	s_nop 0
	global_load_lds_dwordx4 v[226:227], off
	s_waitcnt vmcnt(8)
	s_waitcnt lgkmcnt(0)
	s_setprio 1
	s_barrier
	v_mfma_f32_16x16x32_bf16 v[124:127], v[138:141], v[180:183], v[124:127]
	v_mfma_f32_16x16x32_bf16 v[120:123], v[152:155], v[180:183], v[120:123]
	v_mfma_f32_16x16x32_bf16 v[108:111], v[138:141], v[188:191], v[108:111]
	v_mfma_f32_16x16x32_bf16 v[104:107], v[152:155], v[188:191], v[104:107]
	v_mfma_f32_16x16x32_bf16 v[92:95], v[138:141], v[196:199], v[92:95]
	v_mfma_f32_16x16x32_bf16 v[88:91], v[152:155], v[196:199], v[88:91]
	v_mfma_f32_16x16x32_bf16 v[76:79], v[138:141], v[204:207], v[76:79]
	v_mfma_f32_16x16x32_bf16 v[72:75], v[152:155], v[204:207], v[72:75]
	v_mfma_f32_16x16x32_bf16 v[124:127], v[142:145], v[184:187], v[124:127]
	v_mfma_f32_16x16x32_bf16 v[120:123], v[156:159], v[184:187], v[120:123]
	v_mfma_f32_16x16x32_bf16 v[108:111], v[142:145], v[192:195], v[108:111]
	v_mfma_f32_16x16x32_bf16 v[104:107], v[156:159], v[192:195], v[104:107]
	v_mfma_f32_16x16x32_bf16 v[92:95], v[142:145], v[200:203], v[92:95]
	v_mfma_f32_16x16x32_bf16 v[88:91], v[156:159], v[200:203], v[88:91]
	v_mfma_f32_16x16x32_bf16 v[76:79], v[142:145], v[218:221], v[76:79]
	v_mfma_f32_16x16x32_bf16 v[72:75], v[156:159], v[218:221], v[72:75]
	v_mfma_f32_16x16x32_bf16 v[116:119], v[160:163], v[180:183], v[116:119]
	v_mfma_f32_16x16x32_bf16 v[112:115], v[168:171], v[180:183], v[112:115]
	v_mfma_f32_16x16x32_bf16 v[100:103], v[160:163], v[188:191], v[100:103]
	v_mfma_f32_16x16x32_bf16 v[96:99], v[168:171], v[188:191], v[96:99]
	v_mfma_f32_16x16x32_bf16 v[84:87], v[160:163], v[196:199], v[84:87]
	v_mfma_f32_16x16x32_bf16 v[80:83], v[168:171], v[196:199], v[80:83]
	v_mfma_f32_16x16x32_bf16 v[68:71], v[160:163], v[204:207], v[68:71]
	v_mfma_f32_16x16x32_bf16 v[64:67], v[168:171], v[204:207], v[64:67]
	v_mfma_f32_16x16x32_bf16 v[116:119], v[164:167], v[184:187], v[116:119]
	v_mfma_f32_16x16x32_bf16 v[112:115], v[176:179], v[184:187], v[112:115]
	v_mfma_f32_16x16x32_bf16 v[100:103], v[164:167], v[192:195], v[100:103]
	v_mfma_f32_16x16x32_bf16 v[96:99], v[176:179], v[192:195], v[96:99]
	v_mfma_f32_16x16x32_bf16 v[84:87], v[164:167], v[200:203], v[84:87]
	v_mfma_f32_16x16x32_bf16 v[80:83], v[176:179], v[200:203], v[80:83]
	v_mfma_f32_16x16x32_bf16 v[68:71], v[164:167], v[218:221], v[68:71]
	v_mfma_f32_16x16x32_bf16 v[64:67], v[176:179], v[218:221], v[64:67]
	s_barrier
; #define PG8_STAGE(bufoff, gbase, voff) do { _Pragma("unroll") for (int _i = 0; _i < 2; ++_i) \
;         __builtin_amdgcn_global_load_lds((const unsigned*)((const char*)(gbase) + (voff)[_i]), (PG8_LAS unsigned*)(lds + (bufoff) + ldsw + _i * 8192), 16, 0, 0); } while (0)
; #define PG8_LDA(dst, b, h) do { _Pragma("unroll") for (int m = 0; m < 4; ++m) _Pragma("unroll") for (int k = 0; k < 2; ++k) dst[m][k] = *(const PG8_LAS bf16x8*)(lds + PG8_SA(b, h) + aoff + m * 2048 + k * 1024); } while (0)
; #define PG8_LDB(dst, b, h) do { _Pragma("unroll") for (int n = 0; n < 2; ++n) _Pragma("unroll") for (int k = 0; k < 2; ++k) dst[n][k] = *(const PG8_LAS bf16x8*)(lds + PG8_SB(b, h) + boff + n * 2048 + k * 1024); } while (0)
; template <class Epi, class Sched, bool ALIGN_EPI = false, bool SP2 = false>
; __device__ __forceinline__ void gemm_phase(PG8_LAS unsigned char* lds, const Gemm g, const Sched& S, const Epi& E) {
;     ...
;         for (int t = 0; t < nt; t += 2) {
;             const bool last = (t == nt - 2);
;             const char* a1 = cA + (size_t)(t + 1) * kstep;
;             const char* a2 = last ? nA : cA + (size_t)(t + 2) * kstep; const char* b2 = last ? nB : cB + (size_t)(t + 2) * kstep;
;             const char* a3 = a2 + kstep; const char* b3 = b2 + kstep;
;             if (last && has_next) S.a_ready(nxt);
;             if constexpr (SP2) {
;             PG8_LDB(B0, 0, 0); PG8_LDB(B1, 0, 1); PG8_SCHED; PG8_LDA(At, 0, 0); PG8_STAGE(PG8_SA(1, 1), a1 + hstep, voffA);
;             PG8_WAIT_V(8); PG8_WAIT_L(0); PG8_BAR; PG8_MMA(0, 0, At, B0); PG8_MMA(0, 1, At, B1); PG8_BAR; PG8_SCHED;
;             PG8_LDA(At, 0, 1); PG8_STAGE(PG8_SB(0, 0), b2, voffB); PG8_STAGE(PG8_SB(0, 1), b2 + hstep, voffB); PG8_STAGE(PG8_SA(0, 0), a2, voffA);
;             PG8_WAIT_V(8); PG8_WAIT_L(0); PG8_BAR; PG8_MMA(1, 0, At, B0); PG8_MMA(1, 1, At, B1); PG8_BAR; PG8_SCHED;
;             PG8_LDB(B0, 1, 0); PG8_LDB(B1, 1, 1); PG8_SCHED; PG8_LDA(At, 1, 0); PG8_STAGE(PG8_SA(0, 1), a2 + hstep, voffA);
;             PG8_WAIT_V(8); PG8_WAIT_L(0); PG8_BAR; PG8_MMA(0, 0, At, B0); PG8_MMA(0, 1, At, B1); PG8_BAR; PG8_SCHED;
;             PG8_LDA(At, 1, 1); PG8_STAGE(PG8_SB(1, 0), b3, voffB); PG8_STAGE(PG8_SB(1, 1), b3 + hstep, voffB); PG8_STAGE(PG8_SA(1, 0), a3, voffA);
;             PG8_WAIT_V(8); PG8_WAIT_L(0); PG8_BAR; PG8_MMA(1, 0, At, B0); PG8_MMA(1, 1, At, B1); PG8_BAR; PG8_SCHED;
	s_setprio 0
	s_add_i32 s56, s74, s8
	v_lshl_add_u64 v[172:173], v[172:173], 0, s[4:5]
	s_mov_b32 m0, s56
	ds_read_b128 v[180:183], v150 offset:49152
	ds_read_b128 v[184:187], v150 offset:50176
	ds_read_b128 v[188:191], v150 offset:51200
	ds_read_b128 v[192:195], v150 offset:52224
	ds_read_b128 v[196:199], v150 offset:53248
	ds_read_b128 v[200:203], v150 offset:54272
	ds_read_b128 v[204:207], v150 offset:55296
	ds_read_b128 v[218:221], v150 offset:56320
	global_load_lds_dwordx4 v[172:173], off
	s_add_i32 m0, s56, 0x2000
	s_add_u32 s38, s38, 0x40080
	v_lshl_add_u64 v[172:173], v[208:209], 0, s[4:5]
	s_addc_u32 s39, s39, 0
	s_add_i32 s56, s75, s8
	global_load_lds_dwordx4 v[172:173], off
	v_lshl_add_u64 v[172:173], s[38:39], 0, v[174:175]
	s_mov_b32 m0, s56
	s_nop 0
	global_load_lds_dwordx4 v[172:173], off
	v_lshl_add_u64 v[172:173], s[38:39], 0, v[128:129]
	s_add_i32 m0, s56, 0x2000
	s_nop 0
	global_load_lds_dwordx4 v[172:173], off
	v_lshl_add_u64 v[172:173], v[222:223], 0, s[4:5]
	s_mov_b32 m0, s62
	s_nop 0
	global_load_lds_dwordx4 v[172:173], off
	v_lshl_add_u64 v[172:173], v[224:225], 0, s[4:5]
	s_mov_b32 m0, s63
	s_nop 0
	global_load_lds_dwordx4 v[172:173], off
	s_waitcnt vmcnt(8)
	s_waitcnt lgkmcnt(0)
	s_setprio 1
	s_barrier
	v_mfma_f32_16x16x32_bf16 v[60:63], v[138:141], v[180:183], v[60:63]
	v_mfma_f32_16x16x32_bf16 v[56:59], v[152:155], v[180:183], v[56:59]
	v_mfma_f32_16x16x32_bf16 v[44:47], v[138:141], v[188:191], v[44:47]
	v_mfma_f32_16x16x32_bf16 v[40:43], v[152:155], v[188:191], v[40:43]
	v_mfma_f32_16x16x32_bf16 v[28:31], v[138:141], v[196:199], v[28:31]
	v_mfma_f32_16x16x32_bf16 v[24:27], v[152:155], v[196:199], v[24:27]
	v_mfma_f32_16x16x32_bf16 v[12:15], v[138:141], v[204:207], v[12:15]
	v_mfma_f32_16x16x32_bf16 v[8:11], v[152:155], v[204:207], v[8:11]
	v_mfma_f32_16x16x32_bf16 v[60:63], v[142:145], v[184:187], v[60:63]
	v_mfma_f32_16x16x32_bf16 v[56:59], v[156:159], v[184:187], v[56:59]
	v_mfma_f32_16x16x32_bf16 v[44:47], v[142:145], v[192:195], v[44:47]
	v_mfma_f32_16x16x32_bf16 v[40:43], v[156:159], v[192:195], v[40:43]
	v_mfma_f32_16x16x32_bf16 v[28:31], v[142:145], v[200:203], v[28:31]
	v_mfma_f32_16x16x32_bf16 v[24:27], v[156:159], v[200:203], v[24:27]
	v_mfma_f32_16x16x32_bf16 v[12:15], v[142:145], v[218:221], v[12:15]
	v_mfma_f32_16x16x32_bf16 v[8:11], v[156:159], v[218:221], v[8:11]
	v_mfma_f32_16x16x32_bf16 v[52:55], v[160:163], v[180:183], v[52:55]
	v_mfma_f32_16x16x32_bf16 v[48:51], v[168:171], v[180:183], v[48:51]
	v_mfma_f32_16x16x32_bf16 v[36:39], v[160:163], v[188:191], v[36:39]
	v_mfma_f32_16x16x32_bf16 v[32:35], v[168:171], v[188:191], v[32:35]
	v_mfma_f32_16x16x32_bf16 v[20:23], v[160:163], v[196:199], v[20:23]
	v_mfma_f32_16x16x32_bf16 v[16:19], v[168:171], v[196:199], v[16:19]
	v_mfma_f32_16x16x32_bf16 v[4:7], v[160:163], v[204:207], v[4:7]
	v_mfma_f32_16x16x32_bf16 v[0:3], v[168:171], v[204:207], v[0:3]
	v_mfma_f32_16x16x32_bf16 v[52:55], v[164:167], v[184:187], v[52:55]
	v_mfma_f32_16x16x32_bf16 v[48:51], v[176:179], v[184:187], v[48:51]
	v_mfma_f32_16x16x32_bf16 v[36:39], v[164:167], v[192:195], v[36:39]
	v_mfma_f32_16x16x32_bf16 v[32:35], v[176:179], v[192:195], v[32:35]
	v_mfma_f32_16x16x32_bf16 v[20:23], v[164:167], v[200:203], v[20:23]
	v_mfma_f32_16x16x32_bf16 v[16:19], v[176:179], v[200:203], v[16:19]
	v_mfma_f32_16x16x32_bf16 v[4:7], v[164:167], v[218:221], v[4:7]
	v_mfma_f32_16x16x32_bf16 v[0:3], v[176:179], v[218:221], v[0:3]
	s_barrier
	s_setprio 0
	s_add_i32 s73, s73, 2
	s_add_u32 s0, s0, 0x100
	s_addc_u32 s1, s1, 0
	s_add_u32 s71, s71, 0x100
	s_addc_u32 s72, s72, 0
	s_cmp_gt_u32 s73, 13
	s_cbranch_scc0 .LBB0_1752
	.p2alignl 6, 3212836864

; #define PG8_STAGE(bufoff, gbase, voff) do { _Pragma("unroll") for (int _i = 0; _i < 2; ++_i) \
;         __builtin_amdgcn_global_load_lds((const unsigned*)((const char*)(gbase) + (voff)[_i]), (PG8_LAS unsigned*)(lds + (bufoff) + ldsw + _i * 8192), 16, 0, 0); } while (0)
; #define PG8_LDA(dst, b, h) do { _Pragma("unroll") for (int m = 0; m < 4; ++m) _Pragma("unroll") for (int k = 0; k < 2; ++k) dst[m][k] = *(const PG8_LAS bf16x8*)(lds + PG8_SA(b, h) + aoff + m * 2048 + k * 1024); } while (0)
; #define PG8_LDB(dst, b, h) do { _Pragma("unroll") for (int n = 0; n < 2; ++n) _Pragma("unroll") for (int k = 0; k < 2; ++k) dst[n][k] = *(const PG8_LAS bf16x8*)(lds + PG8_SB(b, h) + boff + n * 2048 + k * 1024); } while (0)
; #define PG8_WAIT_V(n) asm volatile("s_waitcnt vmcnt(" #n ")" ::: "memory")
; #define PG8_WAIT_L(n) asm volatile("s_waitcnt lgkmcnt(" #n ")" ::: "memory")
; #define PG8_BAR __builtin_amdgcn_s_barrier()
; #define PG8_SCHED __builtin_amdgcn_sched_barrier(0)
; template <class Epi, class Sched, bool ALIGN_EPI = false, bool SP2 = false>
; __device__ __forceinline__ void gemm_phase(PG8_LAS unsigned char* lds, const Gemm g, const Sched& S, const Epi& E) {
;     ...
;         const bool has_next = S.next(ui + 1, nxt);
;         const char* nA = has_next ? (const char*)g.A + (size_t)nxt.pm * tstep + (size_t)nxt.pn * g.a_gs : cA; const char* nB = has_next ? (const char*)g.Bt + (size_t)nxt.pn * tstep : cB;
;         for (int t = 0; t < nt; t += 2) {
;             const bool last = (t == nt - 2);
;             const char* a1 = cA + (size_t)(t + 1) * kstep;
;             const char* a2 = last ? nA : cA + (size_t)(t + 2) * kstep; const char* b2 = last ? nB : cB + (size_t)(t + 2) * kstep;
;             const char* a3 = a2 + kstep; const char* b3 = b2 + kstep;
;             if (last && has_next) S.a_ready(nxt);
;             if constexpr (SP2) {
;             PG8_LDB(B0, 0, 0); PG8_LDB(B1, 0, 1); PG8_SCHED; PG8_LDA(At, 0, 0); PG8_STAGE(PG8_SA(1, 1), a1 + hstep, voffA);
;             PG8_WAIT_V(8); PG8_WAIT_L(0); PG8_BAR; PG8_MMA(0, 0, At, B0); PG8_MMA(0, 1, At, B1); PG8_BAR; PG8_SCHED;
;             PG8_LDA(At, 0, 1); PG8_STAGE(PG8_SB(0, 0), b2, voffB); PG8_STAGE(PG8_SB(0, 1), b2 + hstep, voffB); PG8_STAGE(PG8_SA(0, 0), a2, voffA);
;             PG8_WAIT_V(8); PG8_WAIT_L(0); PG8_BAR; PG8_MMA(1, 0, At, B0); PG8_MMA(1, 1, At, B1); PG8_BAR; PG8_SCHED;
.LBB0_1844:
	s_ashr_i32 s49, s48, 31
	s_lshl_b64 s[50:51], s[48:49], 21
	s_add_u32 s50, s14, s50
	s_addc_u32 s51, s15, s51
	s_and_b64 s[52:53], s[42:43], exec
	s_cselect_b32 s49, s51, s1
	s_cselect_b32 s69, s50, s0
	s_ashr_i32 s47, s46, 31
	s_lshl_b64 s[52:53], s[46:47], 21
	s_add_u32 s52, s8, s52
	s_addc_u32 s53, s9, s53
	s_and_b64 s[56:57], s[42:43], exec
	s_cselect_b32 s47, s53, s55
	s_cselect_b32 s70, s52, s54
	s_add_u32 s0, s0, 0x100080
	s_addc_u32 s1, s1, 0
	s_add_u32 s71, s54, 0x100
	s_addc_u32 s72, s55, 0
	s_mov_b32 s73, -2
	s_add_u32 s54, s0, 0xfff00080
	s_addc_u32 s55, s1, -1
	s_add_i32 s74, 0, 0x10000
	s_cmp_eq_u32 s73, 60
	s_cselect_b32 s57, s49, s55
	s_cselect_b32 s56, s69, s54
	s_cselect_b32 s55, s47, s72
	s_cselect_b32 s54, s70, s71
	s_add_i32 s76, 0, 0x14000
	v_add_u32_e32 v140, s74, v189
	v_add_u32_e32 v166, s76, v189
	ds_read_b128 v[128:131], v140
	ds_read_b128 v[132:135], v140 offset:1024
	ds_read_b128 v[136:139], v140 offset:2048
	ds_read_b128 v[140:143], v140 offset:3072
	ds_read_b128 v[144:147], v166
	ds_read_b128 v[148:151], v166 offset:1024
	ds_read_b128 v[162:165], v166 offset:2048
	ds_read_b128 v[166:169], v166 offset:3072
	v_lshl_add_u64 v[208:209], s[0:1], 0, v[158:159]
	s_add_i32 m0, s59, 0xc000
	ds_read_b128 v[170:173], v191
	ds_read_b128 v[176:179], v191 offset:1024
	ds_read_b128 v[180:183], v191 offset:2048
	ds_read_b128 v[184:187], v191 offset:3072
	ds_read_b128 v[192:195], v191 offset:4096
	ds_read_b128 v[196:199], v191 offset:5120
	ds_read_b128 v[200:203], v191 offset:6144
	ds_read_b128 v[204:207], v191 offset:7168
	global_load_lds_dwordx4 v[208:209], off
	v_lshl_add_u64 v[208:209], s[0:1], 0, v[160:161]
	s_add_i32 m0, s59, 0xe000
	s_nop 0
	global_load_lds_dwordx4 v[208:209], off
	s_waitcnt vmcnt(8)
	s_waitcnt lgkmcnt(0)
	s_setprio 1
	s_barrier
	v_mfma_f32_16x16x32_bf16 v[124:127], v[128:131], v[170:173], 0
	v_mfma_f32_16x16x32_bf16 v[120:123], v[136:139], v[170:173], 0
	v_mfma_f32_16x16x32_bf16 v[108:111], v[128:131], v[180:183], 0
	v_mfma_f32_16x16x32_bf16 v[104:107], v[136:139], v[180:183], 0
	v_mfma_f32_16x16x32_bf16 v[92:95], v[128:131], v[192:195], 0
	v_mfma_f32_16x16x32_bf16 v[88:91], v[136:139], v[192:195], 0
	v_mfma_f32_16x16x32_bf16 v[76:79], v[128:131], v[200:203], 0
	v_mfma_f32_16x16x32_bf16 v[72:75], v[136:139], v[200:203], 0
	v_mfma_f32_16x16x32_bf16 v[124:127], v[132:135], v[176:179], v[124:127]
	v_mfma_f32_16x16x32_bf16 v[120:123], v[140:143], v[176:179], v[120:123]
	v_mfma_f32_16x16x32_bf16 v[108:111], v[132:135], v[184:187], v[108:111]
	v_mfma_f32_16x16x32_bf16 v[104:107], v[140:143], v[184:187], v[104:107]
	v_mfma_f32_16x16x32_bf16 v[92:95], v[132:135], v[196:199], v[92:95]
	v_mfma_f32_16x16x32_bf16 v[88:91], v[140:143], v[196:199], v[88:91]
	v_mfma_f32_16x16x32_bf16 v[76:79], v[132:135], v[204:207], v[76:79]
	v_mfma_f32_16x16x32_bf16 v[72:75], v[140:143], v[204:207], v[72:75]
	v_mfma_f32_16x16x32_bf16 v[116:119], v[144:147], v[170:173], 0
	v_mfma_f32_16x16x32_bf16 v[112:115], v[162:165], v[170:173], 0
	v_mfma_f32_16x16x32_bf16 v[100:103], v[144:147], v[180:183], 0
	v_mfma_f32_16x16x32_bf16 v[96:99], v[162:165], v[180:183], 0
	v_mfma_f32_16x16x32_bf16 v[84:87], v[144:147], v[192:195], 0
	v_mfma_f32_16x16x32_bf16 v[80:83], v[162:165], v[192:195], 0
	v_mfma_f32_16x16x32_bf16 v[68:71], v[144:147], v[200:203], 0
	v_mfma_f32_16x16x32_bf16 v[64:67], v[162:165], v[200:203], 0
	v_mfma_f32_16x16x32_bf16 v[116:119], v[148:151], v[176:179], v[116:119]
	v_mfma_f32_16x16x32_bf16 v[112:115], v[166:169], v[176:179], v[112:115]
	v_mfma_f32_16x16x32_bf16 v[100:103], v[148:151], v[184:187], v[100:103]
	v_mfma_f32_16x16x32_bf16 v[96:99], v[166:169], v[184:187], v[96:99]
	v_mfma_f32_16x16x32_bf16 v[84:87], v[148:151], v[196:199], v[84:87]
	v_mfma_f32_16x16x32_bf16 v[80:83], v[166:169], v[196:199], v[80:83]
	v_mfma_f32_16x16x32_bf16 v[68:71], v[148:151], v[204:207], v[68:71]
	v_mfma_f32_16x16x32_bf16 v[64:67], v[166:169], v[204:207], v[64:67]
	s_barrier
	s_setprio 0
	s_add_i32 s74, s74, s58
	v_lshl_add_u64 v[208:209], s[54:55], 0, v[174:175]
	s_mov_b32 m0, s74
	ds_read_b128 v[170:173], v191 offset:16384
	ds_read_b128 v[176:179], v191 offset:17408
	ds_read_b128 v[180:183], v191 offset:18432
	ds_read_b128 v[184:187], v191 offset:19456
	ds_read_b128 v[192:195], v191 offset:20480
	ds_read_b128 v[196:199], v191 offset:21504
	ds_read_b128 v[200:203], v191 offset:22528
	ds_read_b128 v[204:207], v191 offset:23552
	global_load_lds_dwordx4 v[208:209], off
	s_add_i32 m0, s74, 0x2000
	s_add_u32 s74, s54, 0x100000
	v_lshl_add_u64 v[218:219], s[54:55], 0, v[152:153]
	s_addc_u32 s75, s55, 0
	s_add_i32 s76, s76, s58
	global_load_lds_dwordx4 v[218:219], off
	v_lshl_add_u64 v[220:221], s[74:75], 0, v[174:175]
	s_mov_b32 m0, s76
	v_lshl_add_u64 v[222:223], s[56:57], 0, v[154:155]
	global_load_lds_dwordx4 v[220:221], off
	v_lshl_add_u64 v[220:221], s[74:75], 0, v[152:153]
	s_add_i32 m0, s76, 0x2000
	s_nop 0
	global_load_lds_dwordx4 v[220:221], off
	v_lshl_add_u64 v[220:221], s[56:57], 0, v[156:157]
	s_mov_b32 m0, s59
	s_nop 0
	global_load_lds_dwordx4 v[220:221], off
	s_mov_b32 m0, s60
	s_nop 0
	global_load_lds_dwordx4 v[222:223], off
	s_waitcnt vmcnt(8)
	s_waitcnt lgkmcnt(0)
	s_setprio 1
	s_barrier
; #define PG8_STAGE(bufoff, gbase, voff) do { _Pragma("unroll") for (int _i = 0; _i < 2; ++_i) \
;         __builtin_amdgcn_global_load_lds((const unsigned*)((const char*)(gbase) + (voff)[_i]), (PG8_LAS unsigned*)(lds + (bufoff) + ldsw + _i * 8192), 16, 0, 0); } while (0)
; #define PG8_LDA(dst, b, h) do { _Pragma("unroll") for (int m = 0; m < 4; ++m) _Pragma("unroll") for (int k = 0; k < 2; ++k) dst[m][k] = *(const PG8_LAS bf16x8*)(lds + PG8_SA(b, h) + aoff + m * 2048 + k * 1024); } while (0)
; #define PG8_LDB(dst, b, h) do { _Pragma("unroll") for (int n = 0; n < 2; ++n) _Pragma("unroll") for (int k = 0; k < 2; ++k) dst[n][k] = *(const PG8_LAS bf16x8*)(lds + PG8_SB(b, h) + boff + n * 2048 + k * 1024); } while (0)
; #define PG8_MMA(ai, bj, At, Bt) do { __builtin_amdgcn_s_setprio(1); _Pragma("unroll") for (int m = 0; m < 4; ++m) _Pragma("unroll") for (int n = 0; n < 2; ++n) _Pragma("unroll") for (int k = 0; k < 2; ++k) \
;         acc[ai][bj][m][n] = __builtin_amdgcn_mfma_f32_16x16x32_bf16(Bt[n][k], At[m][k], acc[ai][bj][m][n], 0, 0, 0); __builtin_amdgcn_s_setprio(0); } while (0)
; #define PG8_WAIT_V(n) asm volatile("s_waitcnt vmcnt(" #n ")" ::: "memory")
; #define PG8_WAIT_L(n) asm volatile("s_waitcnt lgkmcnt(" #n ")" ::: "memory")
; #define PG8_BAR __builtin_amdgcn_s_barrier()
; #define PG8_SCHED __builtin_amdgcn_sched_barrier(0)
; template <class Epi, class Sched, bool ALIGN_EPI = false, bool SP2 = false>
; __device__ __forceinline__ void gemm_phase(PG8_LAS unsigned char* lds, const Gemm g, const Sched& S, const Epi& E) {
;     ...
;             PG8_WAIT_V(8); PG8_WAIT_L(0); PG8_BAR; PG8_MMA(1, 0, At, B0); PG8_MMA(1, 1, At, B1); PG8_BAR; PG8_SCHED;
;             PG8_LDB(B0, 1, 0); PG8_LDB(B1, 1, 1); PG8_SCHED; PG8_LDA(At, 1, 0); PG8_STAGE(PG8_SA(0, 1), a2 + hstep, voffA);
;             PG8_WAIT_V(8); PG8_WAIT_L(0); PG8_BAR; PG8_MMA(0, 0, At, B0); PG8_MMA(0, 1, At, B1); PG8_BAR; PG8_SCHED;
	v_mfma_f32_16x16x32_bf16 v[60:63], v[128:131], v[170:173], 0
	v_mfma_f32_16x16x32_bf16 v[56:59], v[136:139], v[170:173], 0
	v_mfma_f32_16x16x32_bf16 v[44:47], v[128:131], v[180:183], 0
	v_mfma_f32_16x16x32_bf16 v[40:43], v[136:139], v[180:183], 0
	v_mfma_f32_16x16x32_bf16 v[28:31], v[128:131], v[192:195], 0
	v_mfma_f32_16x16x32_bf16 v[24:27], v[136:139], v[192:195], 0
	v_mfma_f32_16x16x32_bf16 v[12:15], v[128:131], v[200:203], 0
	v_mfma_f32_16x16x32_bf16 v[8:11], v[136:139], v[200:203], 0
	v_mfma_f32_16x16x32_bf16 v[60:63], v[132:135], v[176:179], v[60:63]
	v_mfma_f32_16x16x32_bf16 v[56:59], v[140:143], v[176:179], v[56:59]
	v_mfma_f32_16x16x32_bf16 v[44:47], v[132:135], v[184:187], v[44:47]
	v_mfma_f32_16x16x32_bf16 v[40:43], v[140:143], v[184:187], v[40:43]
	v_mfma_f32_16x16x32_bf16 v[28:31], v[132:135], v[196:199], v[28:31]
	v_mfma_f32_16x16x32_bf16 v[24:27], v[140:143], v[196:199], v[24:27]
	v_mfma_f32_16x16x32_bf16 v[12:15], v[132:135], v[204:207], v[12:15]
	v_mfma_f32_16x16x32_bf16 v[8:11], v[140:143], v[204:207], v[8:11]
	v_mfma_f32_16x16x32_bf16 v[52:55], v[144:147], v[170:173], 0
	v_mfma_f32_16x16x32_bf16 v[48:51], v[162:165], v[170:173], 0
	v_mfma_f32_16x16x32_bf16 v[36:39], v[144:147], v[180:183], 0
	v_mfma_f32_16x16x32_bf16 v[32:35], v[162:165], v[180:183], 0
	v_mfma_f32_16x16x32_bf16 v[20:23], v[144:147], v[192:195], 0
	v_mfma_f32_16x16x32_bf16 v[16:19], v[162:165], v[192:195], 0
	v_mfma_f32_16x16x32_bf16 v[4:7], v[144:147], v[200:203], 0
	v_mfma_f32_16x16x32_bf16 v[0:3], v[162:165], v[200:203], 0
	v_mfma_f32_16x16x32_bf16 v[52:55], v[148:151], v[176:179], v[52:55]
	v_mfma_f32_16x16x32_bf16 v[48:51], v[166:169], v[176:179], v[48:51]
	v_mfma_f32_16x16x32_bf16 v[36:39], v[148:151], v[184:187], v[36:39]
	v_mfma_f32_16x16x32_bf16 v[32:35], v[166:169], v[184:187], v[32:35]
	v_mfma_f32_16x16x32_bf16 v[20:23], v[148:151], v[196:199], v[20:23]
	v_mfma_f32_16x16x32_bf16 v[16:19], v[166:169], v[196:199], v[16:19]
	v_mfma_f32_16x16x32_bf16 v[4:7], v[148:151], v[204:207], v[4:7]
	v_mfma_f32_16x16x32_bf16 v[0:3], v[166:169], v[204:207], v[0:3]
	s_barrier
	s_setprio 0
	s_add_i32 s74, 0, 0x18000
	s_add_i32 s75, 0, 0x1c000
	v_add_u32_e32 v140, s74, v189
	v_add_u32_e32 v166, s75, v189
	ds_read_b128 v[128:131], v140
	ds_read_b128 v[132:135], v140 offset:1024
	ds_read_b128 v[136:139], v140 offset:2048
	ds_read_b128 v[140:143], v140 offset:3072
	ds_read_b128 v[144:147], v166
	ds_read_b128 v[148:151], v166 offset:1024
	ds_read_b128 v[162:165], v166 offset:2048
	ds_read_b128 v[166:169], v166 offset:3072
	s_add_u32 s56, s56, 0x100000
	s_addc_u32 s57, s57, 0
	s_mov_b32 m0, s61
	v_lshl_add_u64 v[224:225], s[56:57], 0, v[156:157]
	ds_read_b128 v[170:173], v191 offset:32768
	ds_read_b128 v[176:179], v191 offset:33792
	ds_read_b128 v[180:183], v191 offset:34816
	ds_read_b128 v[184:187], v191 offset:35840
	ds_read_b128 v[192:195], v191 offset:36864
	ds_read_b128 v[196:199], v191 offset:37888
	ds_read_b128 v[200:203], v191 offset:38912
	ds_read_b128 v[204:207], v191 offset:39936
	global_load_lds_dwordx4 v[224:225], off
	v_lshl_add_u64 v[224:225], s[56:57], 0, v[154:155]
	s_mov_b32 m0, s62
	s_nop 0
	global_load_lds_dwordx4 v[224:225], off
	s_waitcnt vmcnt(8)
	s_waitcnt lgkmcnt(0)
	s_setprio 1
	s_barrier
	v_mfma_f32_16x16x32_bf16 v[124:127], v[128:131], v[170:173], v[124:127]
	v_mfma_f32_16x16x32_bf16 v[120:123], v[136:139], v[170:173], v[120:123]
	v_mfma_f32_16x16x32_bf16 v[108:111], v[128:131], v[180:183], v[108:111]
	v_mfma_f32_16x16x32_bf16 v[104:107], v[136:139], v[180:183], v[104:107]
	v_mfma_f32_16x16x32_bf16 v[92:95], v[128:131], v[192:195], v[92:95]
	v_mfma_f32_16x16x32_bf16 v[88:91], v[136:139], v[192:195], v[88:91]
	v_mfma_f32_16x16x32_bf16 v[76:79], v[128:131], v[200:203], v[76:79]
	v_mfma_f32_16x16x32_bf16 v[72:75], v[136:139], v[200:203], v[72:75]
	v_mfma_f32_16x16x32_bf16 v[124:127], v[132:135], v[176:179], v[124:127]
	v_mfma_f32_16x16x32_bf16 v[120:123], v[140:143], v[176:179], v[120:123]
	v_mfma_f32_16x16x32_bf16 v[108:111], v[132:135], v[184:187], v[108:111]
	v_mfma_f32_16x16x32_bf16 v[104:107], v[140:143], v[184:187], v[104:107]
	v_mfma_f32_16x16x32_bf16 v[92:95], v[132:135], v[196:199], v[92:95]
	v_mfma_f32_16x16x32_bf16 v[88:91], v[140:143], v[196:199], v[88:91]
	v_mfma_f32_16x16x32_bf16 v[76:79], v[132:135], v[204:207], v[76:79]
	v_mfma_f32_16x16x32_bf16 v[72:75], v[140:143], v[204:207], v[72:75]
	v_mfma_f32_16x16x32_bf16 v[116:119], v[144:147], v[170:173], v[116:119]
	v_mfma_f32_16x16x32_bf16 v[112:115], v[162:165], v[170:173], v[112:115]
	v_mfma_f32_16x16x32_bf16 v[100:103], v[144:147], v[180:183], v[100:103]
	v_mfma_f32_16x16x32_bf16 v[96:99], v[162:165], v[180:183], v[96:99]
	v_mfma_f32_16x16x32_bf16 v[84:87], v[144:147], v[192:195], v[84:87]
	v_mfma_f32_16x16x32_bf16 v[80:83], v[162:165], v[192:195], v[80:83]
	v_mfma_f32_16x16x32_bf16 v[68:71], v[144:147], v[200:203], v[68:71]
	v_mfma_f32_16x16x32_bf16 v[64:67], v[162:165], v[200:203], v[64:67]
	v_mfma_f32_16x16x32_bf16 v[116:119], v[148:151], v[176:179], v[116:119]
	v_mfma_f32_16x16x32_bf16 v[112:115], v[166:169], v[176:179], v[112:115]
	v_mfma_f32_16x16x32_bf16 v[100:103], v[148:151], v[184:187], v[100:103]
	v_mfma_f32_16x16x32_bf16 v[96:99], v[166:169], v[184:187], v[96:99]
	v_mfma_f32_16x16x32_bf16 v[84:87], v[148:151], v[196:199], v[84:87]
	v_mfma_f32_16x16x32_bf16 v[80:83], v[166:169], v[196:199], v[80:83]
	v_mfma_f32_16x16x32_bf16 v[68:71], v[148:151], v[204:207], v[68:71]
	v_mfma_f32_16x16x32_bf16 v[64:67], v[166:169], v[204:207], v[64:67]
	s_barrier
; #define PG8_STAGE(bufoff, gbase, voff) do { _Pragma("unroll") for (int _i = 0; _i < 2; ++_i) \
;         __builtin_amdgcn_global_load_lds((const unsigned*)((const char*)(gbase) + (voff)[_i]), (PG8_LAS unsigned*)(lds + (bufoff) + ldsw + _i * 8192), 16, 0, 0); } while (0)
; #define PG8_LDA(dst, b, h) do { _Pragma("unroll") for (int m = 0; m < 4; ++m) _Pragma("unroll") for (int k = 0; k < 2; ++k) dst[m][k] = *(const PG8_LAS bf16x8*)(lds + PG8_SA(b, h) + aoff + m * 2048 + k * 1024); } while (0)
; #define PG8_LDB(dst, b, h) do { _Pragma("unroll") for (int n = 0; n < 2; ++n) _Pragma("unroll") for (int k = 0; k < 2; ++k) dst[n][k] = *(const PG8_LAS bf16x8*)(lds + PG8_SB(b, h) + boff + n * 2048 + k * 1024); } while (0)
; template <class Epi, class Sched, bool ALIGN_EPI = false, bool SP2 = false>
; __device__ __forceinline__ void gemm_phase(PG8_LAS unsigned char* lds, const Gemm g, const Sched& S, const Epi& E) {
;     ...
;         for (int t = 0; t < nt; t += 2) {
;             const bool last = (t == nt - 2);
;             const char* a1 = cA + (size_t)(t + 1) * kstep;
;             const char* a2 = last ? nA : cA + (size_t)(t + 2) * kstep; const char* b2 = last ? nB : cB + (size_t)(t + 2) * kstep;
;             const char* a3 = a2 + kstep; const char* b3 = b2 + kstep;
;             if (last && has_next) S.a_ready(nxt);
;             if constexpr (SP2) {
;             PG8_LDB(B0, 0, 0); PG8_LDB(B1, 0, 1); PG8_SCHED; PG8_LDA(At, 0, 0); PG8_STAGE(PG8_SA(1, 1), a1 + hstep, voffA);
;             PG8_WAIT_V(8); PG8_WAIT_L(0); PG8_BAR; PG8_MMA(0, 0, At, B0); PG8_MMA(0, 1, At, B1); PG8_BAR; PG8_SCHED;
;             PG8_LDA(At, 0, 1); PG8_STAGE(PG8_SB(0, 0), b2, voffB); PG8_STAGE(PG8_SB(0, 1), b2 + hstep, voffB); PG8_STAGE(PG8_SA(0, 0), a2, voffA);
;             PG8_WAIT_V(8); PG8_WAIT_L(0); PG8_BAR; PG8_MMA(1, 0, At, B0); PG8_MMA(1, 1, At, B1); PG8_BAR; PG8_SCHED;
;             PG8_LDB(B0, 1, 0); PG8_LDB(B1, 1, 1); PG8_SCHED; PG8_LDA(At, 1, 0); PG8_STAGE(PG8_SA(0, 1), a2 + hstep, voffA);
;             PG8_WAIT_V(8); PG8_WAIT_L(0); PG8_BAR; PG8_MMA(0, 0, At, B0); PG8_MMA(0, 1, At, B1); PG8_BAR; PG8_SCHED;
;             PG8_LDA(At, 1, 1); PG8_STAGE(PG8_SB(1, 0), b3, voffB); PG8_STAGE(PG8_SB(1, 1), b3 + hstep, voffB); PG8_STAGE(PG8_SA(1, 0), a3, voffA);
;             PG8_WAIT_V(8); PG8_WAIT_L(0); PG8_BAR; PG8_MMA(1, 0, At, B0); PG8_MMA(1, 1, At, B1); PG8_BAR; PG8_SCHED;
	s_setprio 0
	s_add_i32 s56, s74, s58
	v_lshl_add_u64 v[208:209], v[208:209], 0, s[4:5]
	s_mov_b32 m0, s56
	ds_read_b128 v[170:173], v191 offset:49152
	ds_read_b128 v[176:179], v191 offset:50176
	ds_read_b128 v[180:183], v191 offset:51200
	ds_read_b128 v[184:187], v191 offset:52224
	ds_read_b128 v[192:195], v191 offset:53248
	ds_read_b128 v[196:199], v191 offset:54272
	ds_read_b128 v[200:203], v191 offset:55296
	ds_read_b128 v[204:207], v191 offset:56320
	global_load_lds_dwordx4 v[208:209], off
	s_add_i32 m0, s56, 0x2000
	s_add_u32 s54, s54, 0x100080
	v_lshl_add_u64 v[208:209], v[218:219], 0, s[4:5]
	s_addc_u32 s55, s55, 0
	s_add_i32 s56, s75, s58
	global_load_lds_dwordx4 v[208:209], off
	v_lshl_add_u64 v[208:209], s[54:55], 0, v[174:175]
	s_mov_b32 m0, s56
	s_nop 0
	global_load_lds_dwordx4 v[208:209], off
	v_lshl_add_u64 v[208:209], s[54:55], 0, v[152:153]
	s_add_i32 m0, s56, 0x2000
	s_nop 0
	global_load_lds_dwordx4 v[208:209], off
	v_lshl_add_u64 v[208:209], v[220:221], 0, s[4:5]
	s_mov_b32 m0, s64
	s_nop 0
	global_load_lds_dwordx4 v[208:209], off
	v_lshl_add_u64 v[208:209], v[222:223], 0, s[4:5]
	s_mov_b32 m0, s65
	s_nop 0
	global_load_lds_dwordx4 v[208:209], off
	s_waitcnt vmcnt(8)
	s_waitcnt lgkmcnt(0)
	s_setprio 1
	s_barrier
	v_mfma_f32_16x16x32_bf16 v[60:63], v[128:131], v[170:173], v[60:63]
	v_mfma_f32_16x16x32_bf16 v[56:59], v[136:139], v[170:173], v[56:59]
	v_mfma_f32_16x16x32_bf16 v[44:47], v[128:131], v[180:183], v[44:47]
	v_mfma_f32_16x16x32_bf16 v[40:43], v[136:139], v[180:183], v[40:43]
	v_mfma_f32_16x16x32_bf16 v[28:31], v[128:131], v[192:195], v[28:31]
	v_mfma_f32_16x16x32_bf16 v[24:27], v[136:139], v[192:195], v[24:27]
	v_mfma_f32_16x16x32_bf16 v[12:15], v[128:131], v[200:203], v[12:15]
	v_mfma_f32_16x16x32_bf16 v[8:11], v[136:139], v[200:203], v[8:11]
	v_mfma_f32_16x16x32_bf16 v[60:63], v[132:135], v[176:179], v[60:63]
	v_mfma_f32_16x16x32_bf16 v[56:59], v[140:143], v[176:179], v[56:59]
	v_mfma_f32_16x16x32_bf16 v[44:47], v[132:135], v[184:187], v[44:47]
	v_mfma_f32_16x16x32_bf16 v[40:43], v[140:143], v[184:187], v[40:43]
	v_mfma_f32_16x16x32_bf16 v[28:31], v[132:135], v[196:199], v[28:31]
	v_mfma_f32_16x16x32_bf16 v[24:27], v[140:143], v[196:199], v[24:27]
	v_mfma_f32_16x16x32_bf16 v[12:15], v[132:135], v[204:207], v[12:15]
	v_mfma_f32_16x16x32_bf16 v[8:11], v[140:143], v[204:207], v[8:11]
	v_mfma_f32_16x16x32_bf16 v[52:55], v[144:147], v[170:173], v[52:55]
	v_mfma_f32_16x16x32_bf16 v[48:51], v[162:165], v[170:173], v[48:51]
	v_mfma_f32_16x16x32_bf16 v[36:39], v[144:147], v[180:183], v[36:39]
	v_mfma_f32_16x16x32_bf16 v[32:35], v[162:165], v[180:183], v[32:35]
	v_mfma_f32_16x16x32_bf16 v[20:23], v[144:147], v[192:195], v[20:23]
	v_mfma_f32_16x16x32_bf16 v[16:19], v[162:165], v[192:195], v[16:19]
	v_mfma_f32_16x16x32_bf16 v[4:7], v[144:147], v[200:203], v[4:7]
	v_mfma_f32_16x16x32_bf16 v[0:3], v[162:165], v[200:203], v[0:3]
	v_mfma_f32_16x16x32_bf16 v[52:55], v[148:151], v[176:179], v[52:55]
	v_mfma_f32_16x16x32_bf16 v[48:51], v[166:169], v[176:179], v[48:51]
	v_mfma_f32_16x16x32_bf16 v[36:39], v[148:151], v[184:187], v[36:39]
	v_mfma_f32_16x16x32_bf16 v[32:35], v[166:169], v[184:187], v[32:35]
	v_mfma_f32_16x16x32_bf16 v[20:23], v[148:151], v[196:199], v[20:23]
	v_mfma_f32_16x16x32_bf16 v[16:19], v[166:169], v[196:199], v[16:19]
	v_mfma_f32_16x16x32_bf16 v[4:7], v[148:151], v[204:207], v[4:7]
	v_mfma_f32_16x16x32_bf16 v[0:3], v[166:169], v[204:207], v[0:3]
	s_barrier
	s_setprio 0
	s_add_i32 s73, s73, 2
	s_add_u32 s0, s0, 0x100
	s_addc_u32 s1, s1, 0
	s_add_u32 s71, s71, 0x100
	s_addc_u32 s72, s72, 0
	s_cmp_gt_u32 s73, 61
	s_cbranch_scc0 .LBB0_1845
	.p2alignl 6, 3212836864
